# hand-written GLA scan phase: operands prefetched 2 steps ahead into two register sets with loads spread through each step, V/decay staged through LDS 2 steps ahead, uniform wave code, wave-half stagge
# speedup vs baseline: 1.0300x; 1.0300x over previous
; __device__ __forceinline__ f32x16 mfma32(bf16x8 a, bf16x8 b, f32x16 c) { return __builtin_amdgcn_mfma_f32_32x32x16_bf16(a, b, c, 0, 0, 0); }
; #define SCAN_GLOAD(step, G_) do { const int gc_ = SCAN_GC(step); \
;         if (wave < 4) G_ = *(const u32x4*)(BVF + ((((size_t)gc_ * 4 + h) * 16 + sl) * 4 + wave) * 512); \
;         else if (wave == 4) G_ = *(const u32x4*)(DL + ((size_t)gc_ * 4 + h) * 256 + lane * 4); } while (0)
; #define SCAN_GSTORE(buf, G_) do { if (wave < 4) *(u32x4*)(vst + (((buf) * 4 + wave) * 64 + lane) * 16) = G_; \
;         else if (wave == 4) *(u32x4*)(dst + (buf) * 1024 + lane * 16) = G_; } while (0)
; __device__ __forceinline__ void phase_scan(const Args& a, unsigned char* smem, int tid, int lane, int wave) {
;     ...
;         f32x16 S;
; #pragma unroll
;         for (int i = 0; i < 16; ++i) S[i] = 0.f;
;         bf16x8 vB[4], qeA[4], atA; f32x4 dl[4];
;         bf16x8 nqe[4], nat;
;         u32x4 gcur = {0u, 0u, 0u, 0u}, gnxt = {0u, 0u, 0u, 0u};
;     ...
;         const unsigned char* scb; unsigned scsg;
;         { const int q16s = sl * 16 + (lane & 15);
;           if (wave == 5) { if (lane < 16) { scb = (const unsigned char*)KDT + (size_t)h * 32768 + (size_t)q16s * 128; scsg = 131072u; }
;                            else if (lane < 32) { scb = (const unsigned char*)QE + (size_t)h * 512 + (size_t)(q16s >> 2) * 2048 + (q16s & 3) * 128; scsg = 131072u; }
;                            else if (lane < 36) { scb = (const unsigned char*)ATT + (size_t)h * 8192 + (size_t)(sl * 4 + lane - 32) * 128; scsg = 32768u; }
;                            else { scb = (const unsigned char*)DL + (size_t)h * 1024 + (lane & 7) * 128; scsg = 4096u; } }
;           else if (wave == 6) { scb = (const unsigned char*)(a.ws + WS_BVT) + (size_t)(h * 16 + sl) * 4096 + (size_t)(lane & 31) * 128; scsg = 262144u; }
;           else { scb = (const unsigned char*)DL + (size_t)h * 1024; scsg = 0u; } }
;         unsigned scA = 0u, scB = 0u;
;         __syncthreads();
;         SCAN_GLOAD(0, gcur); SCAN_GSTORE(0, gcur);
;         SCAN_GLOAD(1, gcur);
;         SCAN_LOAD(0, qeA, atA);
;         __syncthreads();
;         SCAN_LREAD(0, vB, dl);
;         __builtin_amdgcn_s_waitcnt(0x0F70);
;     ...
;             for (int i = 0; i < 16; ++i) S[i] *= dl[i >> 2][i & 3];
; #pragma unroll
;             for (int ks = 0; ks < 4; ++ks) S = mfma32(kdA[ks], vB[ks], S);
.Lscan_gb_done:
	v_lshrrev_b32_e32 v251, 5, v160
	v_lshlrev_b32_e32 v251, 4, v251
	s_lshl_b32 s41, s0, 7
	v_add_u32_e32 v251, s41, v251
	s_cmp_eq_u32 s17, 1
	s_cselect_b32 s40, 3, 0
	s_lshl_b32 s41, s15, 2
	s_add_i32 s40, s40, s41
	s_addk_i32 s40, 0x200
	s_lshl_b32 s41, s40, 17
	s_add_u32 s32, s20, s41
	s_addc_u32 s33, s21, 0
	s_lshl_b32 s41, s40, 18
	s_add_u32 s34, s48, s41
	s_addc_u32 s35, s49, 0
	s_lshl_b32 s41, s40, 12
	s_add_u32 s36, s46, s41
	s_addc_u32 s37, s47, 0
	global_load_dwordx4 v[16:19], v235, s[32:33]
	global_load_dwordx4 v[20:23], v235, s[32:33] offset:1024
	global_load_dwordx4 v[24:27], v235, s[32:33] offset:2048
	global_load_dwordx4 v[28:31], v235, s[32:33] offset:3072
	global_load_dwordx4 v[80:83], v234, s[34:35]
	global_load_dwordx4 v[84:87], v234, s[34:35] offset:1024
	global_load_dwordx4 v[88:91], v234, s[34:35] offset:2048
	global_load_dwordx4 v[92:95], v234, s[34:35] offset:3072
	global_load_dwordx4 v[144:147], v251, s[36:37]
	global_load_dwordx4 v[148:151], v251, s[36:37] offset:32
	global_load_dwordx4 v[152:155], v251, s[36:37] offset:64
	global_load_dwordx4 v[156:159], v251, s[36:37] offset:96
	s_cmp_eq_u32 s17, 1
	s_cselect_b32 s40, 2, 1
	s_lshl_b32 s41, s15, 2
	s_add_i32 s40, s40, s41
	s_addk_i32 s40, 0x200
	s_lshl_b32 s41, s40, 17
	s_add_u32 s32, s20, s41
	s_addc_u32 s33, s21, 0
	s_lshl_b32 s41, s40, 18
	s_add_u32 s34, s48, s41
	s_addc_u32 s35, s49, 0
	s_lshl_b32 s41, s40, 12
	s_add_u32 s36, s46, s41
	s_addc_u32 s37, s47, 0
	global_load_dwordx4 v[32:35], v235, s[32:33]
	global_load_dwordx4 v[36:39], v235, s[32:33] offset:1024
	global_load_dwordx4 v[40:43], v235, s[32:33] offset:2048
	global_load_dwordx4 v[44:47], v235, s[32:33] offset:3072
	global_load_dwordx4 v[96:99], v234, s[34:35]
	global_load_dwordx4 v[100:103], v234, s[34:35] offset:1024
	global_load_dwordx4 v[104:107], v234, s[34:35] offset:2048
	global_load_dwordx4 v[108:111], v234, s[34:35] offset:3072
	global_load_dwordx4 v[162:165], v251, s[36:37]
	global_load_dwordx4 v[166:169], v251, s[36:37] offset:32
	global_load_dwordx4 v[170:173], v251, s[36:37] offset:64
	global_load_dwordx4 v[174:177], v251, s[36:37] offset:96
	s_cmp_eq_u32 s17, 1
	s_cselect_b32 s40, 1, 2
	s_lshl_b32 s41, s15, 2
	s_add_i32 s40, s40, s41
	s_addk_i32 s40, 0x200
	s_lshl_b32 s41, s40, 17
	s_add_u32 s32, s20, s41
	s_addc_u32 s33, s21, 0
	s_lshl_b32 s41, s40, 18
	s_add_u32 s34, s48, s41
	s_addc_u32 s35, s49, 0
	s_lshl_b32 s41, s40, 12
	s_add_u32 s36, s46, s41
	s_addc_u32 s37, s47, 0
	global_load_dwordx4 v[48:51], v235, s[32:33]
	global_load_dwordx4 v[52:55], v235, s[32:33] offset:1024
	global_load_dwordx4 v[56:59], v235, s[32:33] offset:2048
	global_load_dwordx4 v[60:63], v235, s[32:33] offset:3072
	global_load_dwordx4 v[112:115], v234, s[34:35]
	global_load_dwordx4 v[116:119], v234, s[34:35] offset:1024
	global_load_dwordx4 v[120:123], v234, s[34:35] offset:2048
	global_load_dwordx4 v[124:127], v234, s[34:35] offset:3072
	global_load_dwordx4 v[178:181], v251, s[36:37]
	global_load_dwordx4 v[182:185], v251, s[36:37] offset:32
	global_load_dwordx4 v[186:189], v251, s[36:37] offset:64
	global_load_dwordx4 v[190:193], v251, s[36:37] offset:96
	s_cmp_eq_u32 s17, 1
	s_cselect_b32 s40, 0, 3
	s_lshl_b32 s41, s15, 2
	s_add_i32 s40, s40, s41
	s_addk_i32 s40, 0x200
	s_lshl_b32 s41, s40, 17
	s_add_u32 s32, s20, s41
	s_addc_u32 s33, s21, 0
	s_lshl_b32 s41, s40, 18
	s_add_u32 s34, s48, s41
	s_addc_u32 s35, s49, 0
	s_lshl_b32 s41, s40, 12
	s_add_u32 s36, s46, s41
	s_addc_u32 s37, s47, 0
	global_load_dwordx4 v[64:67], v235, s[32:33]
	global_load_dwordx4 v[68:71], v235, s[32:33] offset:1024
	global_load_dwordx4 v[72:75], v235, s[32:33] offset:2048
	global_load_dwordx4 v[76:79], v235, s[32:33] offset:3072
	global_load_dwordx4 v[128:131], v234, s[34:35]
	global_load_dwordx4 v[132:135], v234, s[34:35] offset:1024
	global_load_dwordx4 v[136:139], v234, s[34:35] offset:2048
	global_load_dwordx4 v[140:143], v234, s[34:35] offset:3072
	global_load_dwordx4 v[194:197], v251, s[36:37]
	global_load_dwordx4 v[198:201], v251, s[36:37] offset:32
	global_load_dwordx4 v[202:205], v251, s[36:37] offset:64
	global_load_dwordx4 v[206:209], v251, s[36:37] offset:96
	s_lshl_b32 s41, s0, 10
	v_add_u32_e32 v251, s41, v234
	s_waitcnt vmcnt(36)
	v_mfma_f32_32x32x16_bf16 v[0:15], v[16:19], v[80:83], 0
	v_mfma_f32_32x32x16_bf16 v[0:15], v[20:23], v[84:87], v[0:15]
	v_mfma_f32_32x32x16_bf16 v[0:15], v[24:27], v[88:91], v[0:15]
	v_mfma_f32_32x32x16_bf16 v[0:15], v[28:31], v[92:95], v[0:15]
	s_waitcnt vmcnt(24)
	s_nop 15
	v_pk_mul_f32 v[0:1], v[162:163], v[0:1]
	v_pk_mul_f32 v[2:3], v[164:165], v[2:3]
	v_pk_mul_f32 v[4:5], v[166:167], v[4:5]
	v_pk_mul_f32 v[6:7], v[168:169], v[6:7]
	v_pk_mul_f32 v[8:9], v[170:171], v[8:9]
	v_pk_mul_f32 v[10:11], v[172:173], v[10:11]
	v_pk_mul_f32 v[12:13], v[174:175], v[12:13]
	v_pk_mul_f32 v[14:15], v[176:177], v[14:15]
	s_nop 1
	v_mfma_f32_32x32x16_bf16 v[0:15], v[32:35], v[96:99], v[0:15]
	v_mfma_f32_32x32x16_bf16 v[0:15], v[36:39], v[100:103], v[0:15]
	v_mfma_f32_32x32x16_bf16 v[0:15], v[40:43], v[104:107], v[0:15]
	v_mfma_f32_32x32x16_bf16 v[0:15], v[44:47], v[108:111], v[0:15]
	s_waitcnt vmcnt(12)
	s_nop 15
	v_pk_mul_f32 v[0:1], v[178:179], v[0:1]
	v_pk_mul_f32 v[2:3], v[180:181], v[2:3]
	v_pk_mul_f32 v[4:5], v[182:183], v[4:5]
	v_pk_mul_f32 v[6:7], v[184:185], v[6:7]
	v_pk_mul_f32 v[8:9], v[186:187], v[8:9]
	v_pk_mul_f32 v[10:11], v[188:189], v[10:11]
	v_pk_mul_f32 v[12:13], v[190:191], v[12:13]
	v_pk_mul_f32 v[14:15], v[192:193], v[14:15]
	s_nop 1
	v_mfma_f32_32x32x16_bf16 v[0:15], v[48:51], v[112:115], v[0:15]
	v_mfma_f32_32x32x16_bf16 v[0:15], v[52:55], v[116:119], v[0:15]
	v_mfma_f32_32x32x16_bf16 v[0:15], v[56:59], v[120:123], v[0:15]
	v_mfma_f32_32x32x16_bf16 v[0:15], v[60:63], v[124:127], v[0:15]
	s_waitcnt vmcnt(0)
	s_nop 15
	v_pk_mul_f32 v[0:1], v[194:195], v[0:1]
	v_pk_mul_f32 v[2:3], v[196:197], v[2:3]
	v_pk_mul_f32 v[4:5], v[198:199], v[4:5]
	v_pk_mul_f32 v[6:7], v[200:201], v[6:7]
	v_pk_mul_f32 v[8:9], v[202:203], v[8:9]
	v_pk_mul_f32 v[10:11], v[204:205], v[10:11]
	v_pk_mul_f32 v[12:13], v[206:207], v[12:13]
	v_pk_mul_f32 v[14:15], v[208:209], v[14:15]
	s_nop 1
	v_mfma_f32_32x32x16_bf16 v[0:15], v[64:67], v[128:131], v[0:15]
	v_mfma_f32_32x32x16_bf16 v[0:15], v[68:71], v[132:135], v[0:15]
	v_mfma_f32_32x32x16_bf16 v[0:15], v[72:75], v[136:139], v[0:15]
	v_mfma_f32_32x32x16_bf16 v[0:15], v[76:79], v[140:143], v[0:15]
	s_nop 15
	s_nop 3
	s_mov_b32 s30, 0
	s_mov_b32 s42, 0
	s_min_u32 s42, s42, 0xff
	s_mul_i32 s42, s42, s29
	s_add_i32 s42, s42, s28
	v_mad_u64_u32 v[194:195], s[44:45], v238, s42, v[236:237]
	global_load_dwordx4 v[204:207], v[194:195], off
	s_mov_b32 s42, 1
	s_min_u32 s42, s42, 0xff
	s_mul_i32 s42, s42, s29
	s_add_i32 s42, s42, s28
	v_mad_u64_u32 v[194:195], s[44:45], v238, s42, v[236:237]
	global_load_dwordx4 v[208:211], v[194:195], off
	s_waitcnt vmcnt(0)
	s_barrier
; __device__ __forceinline__ void phase_scan(const Args& a, unsigned char* smem, int tid, int lane, int wave) {
;     ...
;         auto stepf = [&](const int step, unsigned& sc_issue, unsigned& sc_consume) __attribute__((always_inline)) {
;             const int nstep = step < 259 ? step + 1 : step, n2 = step < 258 ? step + 2 : 259;
;             SCAN_LOAD(nstep, nqe, nat);
;             SCAN_GLOAD(n2, gnxt);
;     ...
;             { int ss = step + SCOUT; ss = ss > 259 ? 259 : ss; const int gcs = SCAN_GC(ss); sc_issue = *(const unsigned*)(scb + (size_t)gcs * scsg); }
;     ...
;             const int gc = SCAN_GC(step); const size_t row0 = (size_t)gc * 64;
;             bf16x8 kdA[4];
;             { const bf16_t* kp = KDT + (((size_t)gc * 4 + h) * 8 + kb) * 2048 + lane * 8;
; #pragma unroll
;               for (int q = 0; q < 4; ++q) kdA[q] = *(const bf16x8*)(kp + 512 * q); }
;             const int rbuf = step & 1, nbuf = rbuf ^ 1;
;             if (gc < 512) {
;                 u32x4 s0, s1;
;                 s0.x = pk2(S[0], S[1]); s0.y = pk2(S[2], S[3]); s0.z = pk2(S[4], S[5]); s0.w = pk2(S[6], S[7]);
;                 s1.x = pk2(S[8], S[9]); s1.y = pk2(S[10], S[11]); s1.z = pk2(S[12], S[13]); s1.w = pk2(S[14], S[15]);
;                 const bf16x8 sb0 = __builtin_bit_cast(bf16x8, s0), sb1 = __builtin_bit_cast(bf16x8, s1);
;                 f32x16 o0, o1;
; #pragma unroll
;                 for (int i = 0; i < 16; ++i) { o0[i] = 0.f; o1[i] = 0.f; }
;                 o0 = mfma32(qeA[0], sb0, o0); o0 = mfma32(qeA[1], sb1, o0);
;                 o1 = mfma32(qeA[2], sb0, o1); o1 = mfma32(qeA[3], sb1, o1);
;                 const int w3 = wave & 3;
;                 const bf16x8 vs = w3 == 0 ? vB[0] : (w3 == 1 ? vB[1] : (w3 == 2 ? vB[2] : vB[3]));
;                 if (wave < 4) o0 = mfma32(atA, vs, o0); else o1 = mfma32(atA, vs, o1);
;                 unsigned* rb = red + (size_t)(rbuf * 8 + wave) * 1024 + lane; unsigned* rbx = red + (size_t)(rbuf * 8 + wave) * 1024 + (lane ^ 32);
; #pragma unroll
;                 for (int i = 0; i < 8; ++i) { unsigned* w_ = (i & 1) ? rbx : rb; w_[i * 64] = pk2(o0[2 * i], o0[2 * i + 1]); w_[512 + i * 64] = pk2(o1[2 * i], o1[2 * i + 1]); }
;             }
;             SCAN_GSTORE(nbuf, gcur);
;             __syncthreads();
;             if (gc < 512) {
	ds_write_b128 v239, v[204:207]
	ds_write_b128 v240, v[208:211]
	s_waitcnt lgkmcnt(0)
	s_barrier
	ds_read_b128 v[128:131], v246 offset:0
	ds_read_b128 v[132:135], v246 offset:1024
	ds_read_b128 v[136:139], v246 offset:2048
	ds_read_b128 v[140:143], v246 offset:3072
	ds_read_b128 v[196:199], v248 offset:0
	ds_read_b128 v[162:165], v247 offset:0
	ds_read_b128 v[166:169], v247 offset:32
	ds_read_b128 v[170:173], v247 offset:64
	ds_read_b128 v[174:177], v247 offset:96
	s_lshl_b32 s53, s29, 17
	s_lshl_b32 s54, s29, 15
	s_lshl_b32 s55, s29, 18
	s_ashr_i32 s56, s29, 31
	s_mov_b32 s40, 0
	s_mul_i32 s40, s40, s29
	s_add_i32 s40, s40, s28
	s_lshl_b32 s41, s40, 17
	s_add_u32 s32, s20, s41
	s_addc_u32 s33, s21, 0
	s_add_u32 s34, s22, s41
	s_addc_u32 s35, s23, 0
	s_lshl_b32 s41, s40, 15
	s_add_u32 s36, s24, s41
	s_addc_u32 s37, s25, 0
	s_add_i32 s42, s31, -2
	s_mul_i32 s42, s42, s29
	s_add_i32 s42, s42, s28
	v_mad_u64_u32 v[194:195], s[44:45], v238, s42, v[236:237]
	v_mul_lo_u32 v254, v238, s29
	v_ashrrev_i32_e32 v255, 31, v254
	s_lshl_b32 s40, s28, 18
	s_add_u32 s38, s26, s40
	s_addc_u32 s39, s27, 0
	global_load_dwordx4 v[204:207], v[194:195], off
	v_lshl_add_u64 v[194:195], v[194:195], 0, v[254:255]
	global_load_dwordx4 v[76:79], v235, s[32:33]
	global_load_dwordx4 v[80:83], v235, s[32:33] offset:1024
	global_load_dwordx4 v[84:87], v235, s[32:33] offset:2048
	global_load_dwordx4 v[88:91], v235, s[32:33] offset:3072
	global_load_dwordx4 v[56:59], v232, s[34:35] offset:-4096
	global_load_dwordx4 v[60:63], v232, s[34:35]
	global_load_dwordx4 v[64:67], v233, s[34:35] offset:-4096
	global_load_dwordx4 v[68:71], v233, s[34:35]
	global_load_dwordx4 v[72:75], v251, s[36:37]
	s_add_u32 s32, s32, s53
	s_addc_u32 s33, s33, s56
	s_add_u32 s34, s34, s53
	s_addc_u32 s35, s35, s56
	s_add_u32 s36, s36, s54
	s_addc_u32 s37, s37, s56
	global_load_dwordx4 v[208:211], v[194:195], off
	v_lshl_add_u64 v[194:195], v[194:195], 0, v[254:255]
	global_load_dwordx4 v[112:115], v235, s[32:33]
	global_load_dwordx4 v[116:119], v235, s[32:33] offset:1024
	global_load_dwordx4 v[120:123], v235, s[32:33] offset:2048
	global_load_dwordx4 v[124:127], v235, s[32:33] offset:3072
	global_load_dwordx4 v[92:95], v232, s[34:35] offset:-4096
	global_load_dwordx4 v[96:99], v232, s[34:35]
	global_load_dwordx4 v[100:103], v233, s[34:35] offset:-4096
	global_load_dwordx4 v[104:107], v233, s[34:35]
	global_load_dwordx4 v[108:111], v251, s[36:37]
	s_add_u32 s32, s32, s53
	s_addc_u32 s33, s33, s56
	s_add_u32 s34, s34, s53
	s_addc_u32 s35, s35, s56
	s_add_u32 s36, s36, s54
	s_addc_u32 s37, s37, s56
	s_waitcnt lgkmcnt(0)
	s_barrier
	s_cmp_lt_u32 s0, 4
	s_cbranch_scc0 .Lscan_pathB
	s_waitcnt vmcnt(10)
	ds_write_b128 v239, v[204:207]
	global_load_dwordx4 v[204:207], v[194:195], off
	v_lshl_add_u64 v[194:195], v[194:195], 0, v[254:255]
	v_cvt_pk_bf16_f32 v48, v0, v1
	v_cvt_pk_bf16_f32 v49, v2, v3
	v_cvt_pk_bf16_f32 v50, v4, v5
	v_cvt_pk_bf16_f32 v51, v6, v7
	v_cvt_pk_bf16_f32 v52, v8, v9
	v_cvt_pk_bf16_f32 v53, v10, v11
	v_cvt_pk_bf16_f32 v54, v12, v13
	v_cvt_pk_bf16_f32 v55, v14, v15
	v_mfma_f32_32x32x16_bf16 v[16:31], v[56:59], v[48:51], 0
	v_pk_mul_f32 v[0:1], v[162:163], v[0:1]
	v_pk_mul_f32 v[2:3], v[164:165], v[2:3]
	v_pk_mul_f32 v[4:5], v[166:167], v[4:5]
	v_mfma_f32_32x32x16_bf16 v[32:47], v[64:67], v[48:51], 0
	v_pk_mul_f32 v[6:7], v[168:169], v[6:7]
	v_pk_mul_f32 v[8:9], v[170:171], v[8:9]
	v_pk_mul_f32 v[10:11], v[172:173], v[10:11]
	v_mfma_f32_32x32x16_bf16 v[16:31], v[60:63], v[52:55], v[16:31]
	v_pk_mul_f32 v[12:13], v[174:175], v[12:13]
	v_pk_mul_f32 v[14:15], v[176:177], v[14:15]
	v_mfma_f32_32x32x16_bf16 v[32:47], v[68:71], v[52:55], v[32:47]
	v_mfma_f32_32x32x16_bf16 v[16:31], v[72:75], v[196:199], v[16:31]
	v_mfma_f32_32x32x16_bf16 v[0:15], v[76:79], v[128:131], v[0:15]
	v_mfma_f32_32x32x16_bf16 v[0:15], v[80:83], v[132:135], v[0:15]
	v_mfma_f32_32x32x16_bf16 v[0:15], v[84:87], v[136:139], v[0:15]
	v_mfma_f32_32x32x16_bf16 v[0:15], v[88:91], v[140:143], v[0:15]
	ds_read_b128 v[144:147], v246 offset:4096
	global_load_dwordx4 v[76:79], v235, s[32:33]
	ds_read_b128 v[148:151], v246 offset:5120
	ds_read_b128 v[152:155], v246 offset:6144
	ds_read_b128 v[156:159], v246 offset:7168
	ds_read_b128 v[200:203], v248 offset:4096
	global_load_dwordx4 v[80:83], v235, s[32:33] offset:1024
	ds_read_b128 v[178:181], v247 offset:1024
	ds_read_b128 v[182:185], v247 offset:1056
	ds_read_b128 v[186:189], v247 offset:1088
	ds_read_b128 v[190:193], v247 offset:1120
	global_load_dwordx4 v[84:87], v235, s[32:33] offset:2048
	v_cvt_pk_bf16_f32 v16, v16, v17
	v_cvt_pk_bf16_f32 v18, v18, v19
	v_cvt_pk_bf16_f32 v20, v20, v21
	global_load_dwordx4 v[88:91], v235, s[32:33] offset:3072
	v_cvt_pk_bf16_f32 v22, v22, v23
	v_cvt_pk_bf16_f32 v24, v24, v25
	v_cvt_pk_bf16_f32 v26, v26, v27
	v_cvt_pk_bf16_f32 v28, v28, v29
	global_load_dwordx4 v[56:59], v232, s[34:35] offset:-4096
	v_cvt_pk_bf16_f32 v30, v30, v31
	ds_write2st64_b32 v241, v16, v20 offset0:0 offset1:2
	ds_write2st64_b32 v242, v18, v22 offset0:1 offset1:3
	ds_write2st64_b32 v241, v24, v28 offset0:4 offset1:6
	global_load_dwordx4 v[60:63], v232, s[34:35]
	ds_write2st64_b32 v242, v26, v30 offset0:5 offset1:7
	v_cvt_pk_bf16_f32 v32, v32, v33
	v_cvt_pk_bf16_f32 v34, v34, v35
	global_load_dwordx4 v[64:67], v233, s[34:35] offset:-4096
	v_cvt_pk_bf16_f32 v36, v36, v37
	v_cvt_pk_bf16_f32 v38, v38, v39
	v_cvt_pk_bf16_f32 v40, v40, v41
	v_cvt_pk_bf16_f32 v42, v42, v43
	global_load_dwordx4 v[68:71], v233, s[34:35]
	v_cvt_pk_bf16_f32 v44, v44, v45
	v_cvt_pk_bf16_f32 v46, v46, v47
	ds_write2st64_b32 v243, v32, v36 offset0:0 offset1:2
	ds_write2st64_b32 v244, v34, v38 offset0:1 offset1:3
	global_load_dwordx4 v[72:75], v251, s[36:37]
	ds_write2st64_b32 v243, v40, v44 offset0:4 offset1:6
	ds_write2st64_b32 v244, v42, v46 offset0:5 offset1:7
	s_add_u32 s32, s32, s53
	s_addc_u32 s33, s33, s56
	s_add_u32 s34, s34, s53
	s_addc_u32 s35, s35, s56
	s_add_u32 s36, s36, s54
	s_addc_u32 s37, s37, s56
	s_waitcnt lgkmcnt(0)
	s_barrier
; __device__ __forceinline__ void phase_scan(const Args& a, unsigned char* smem, int tid, int lane, int wave) {
;     ...
;         auto stepf = [&](const int step, unsigned& sc_issue, unsigned& sc_consume) __attribute__((always_inline)) {
;             const int nstep = step < 259 ? step + 1 : step, n2 = step < 258 ? step + 2 : 259;
;             SCAN_LOAD(nstep, nqe, nat);
;             SCAN_GLOAD(n2, gnxt);
;     ...
;             { int ss = step + SCOUT; ss = ss > 259 ? 259 : ss; const int gcs = SCAN_GC(ss); sc_issue = *(const unsigned*)(scb + (size_t)gcs * scsg); }
;     ...
;             const int gc = SCAN_GC(step); const size_t row0 = (size_t)gc * 64;
;             bf16x8 kdA[4];
;             { const bf16_t* kp = KDT + (((size_t)gc * 4 + h) * 8 + kb) * 2048 + lane * 8;
; #pragma unroll
;               for (int q = 0; q < 4; ++q) kdA[q] = *(const bf16x8*)(kp + 512 * q); }
;             const int rbuf = step & 1, nbuf = rbuf ^ 1;
;             if (gc < 512) {
;                 u32x4 s0, s1;
;                 s0.x = pk2(S[0], S[1]); s0.y = pk2(S[2], S[3]); s0.z = pk2(S[4], S[5]); s0.w = pk2(S[6], S[7]);
;                 s1.x = pk2(S[8], S[9]); s1.y = pk2(S[10], S[11]); s1.z = pk2(S[12], S[13]); s1.w = pk2(S[14], S[15]);
;                 const bf16x8 sb0 = __builtin_bit_cast(bf16x8, s0), sb1 = __builtin_bit_cast(bf16x8, s1);
;                 f32x16 o0, o1;
; #pragma unroll
;                 for (int i = 0; i < 16; ++i) { o0[i] = 0.f; o1[i] = 0.f; }
;                 o0 = mfma32(qeA[0], sb0, o0); o0 = mfma32(qeA[1], sb1, o0);
;                 o1 = mfma32(qeA[2], sb0, o1); o1 = mfma32(qeA[3], sb1, o1);
;                 const int w3 = wave & 3;
;                 const bf16x8 vs = w3 == 0 ? vB[0] : (w3 == 1 ? vB[1] : (w3 == 2 ? vB[2] : vB[3]));
;                 if (wave < 4) o0 = mfma32(atA, vs, o0); else o1 = mfma32(atA, vs, o1);
;                 unsigned* rb = red + (size_t)(rbuf * 8 + wave) * 1024 + lane; unsigned* rbx = red + (size_t)(rbuf * 8 + wave) * 1024 + (lane ^ 32);
; #pragma unroll
;                 for (int i = 0; i < 8; ++i) { unsigned* w_ = (i & 1) ? rbx : rb; w_[i * 64] = pk2(o0[2 * i], o0[2 * i + 1]); w_[512 + i * 64] = pk2(o1[2 * i], o1[2 * i + 1]); }
;             }
;             SCAN_GSTORE(nbuf, gcur);
;             __syncthreads();
;             if (gc < 512) {
	s_waitcnt vmcnt(10)
	ds_write_b128 v240, v[208:211]
	global_load_dwordx4 v[208:211], v[194:195], off
	v_lshl_add_u64 v[194:195], v[194:195], 0, v[254:255]
	v_cvt_pk_bf16_f32 v48, v0, v1
	v_cvt_pk_bf16_f32 v49, v2, v3
	v_cvt_pk_bf16_f32 v50, v4, v5
	v_cvt_pk_bf16_f32 v51, v6, v7
	v_cvt_pk_bf16_f32 v52, v8, v9
	v_cvt_pk_bf16_f32 v53, v10, v11
	v_cvt_pk_bf16_f32 v54, v12, v13
	v_cvt_pk_bf16_f32 v55, v14, v15
	v_mfma_f32_32x32x16_bf16 v[16:31], v[92:95], v[48:51], 0
	v_pk_mul_f32 v[0:1], v[178:179], v[0:1]
	v_pk_mul_f32 v[2:3], v[180:181], v[2:3]
	v_pk_mul_f32 v[4:5], v[182:183], v[4:5]
	v_mfma_f32_32x32x16_bf16 v[32:47], v[100:103], v[48:51], 0
	v_pk_mul_f32 v[6:7], v[184:185], v[6:7]
	v_pk_mul_f32 v[8:9], v[186:187], v[8:9]
	v_pk_mul_f32 v[10:11], v[188:189], v[10:11]
	v_mfma_f32_32x32x16_bf16 v[16:31], v[96:99], v[52:55], v[16:31]
	v_pk_mul_f32 v[12:13], v[190:191], v[12:13]
	v_pk_mul_f32 v[14:15], v[192:193], v[14:15]
	v_mfma_f32_32x32x16_bf16 v[32:47], v[104:107], v[52:55], v[32:47]
	v_mfma_f32_32x32x16_bf16 v[16:31], v[108:111], v[200:203], v[16:31]
	v_mfma_f32_32x32x16_bf16 v[0:15], v[112:115], v[144:147], v[0:15]
	v_mfma_f32_32x32x16_bf16 v[0:15], v[116:119], v[148:151], v[0:15]
	v_mfma_f32_32x32x16_bf16 v[0:15], v[120:123], v[152:155], v[0:15]
	v_mfma_f32_32x32x16_bf16 v[0:15], v[124:127], v[156:159], v[0:15]
	ds_read2st64_b64 v[212:215], v245 offset0:0 offset1:8
	ds_read2st64_b64 v[216:219], v245 offset0:16 offset1:24
	ds_read2st64_b64 v[220:223], v245 offset0:32 offset1:40
	ds_read2st64_b64 v[224:227], v245 offset0:48 offset1:56
	ds_read_b128 v[128:131], v246 offset:0
	global_load_dwordx4 v[112:115], v235, s[32:33]
	ds_read_b128 v[132:135], v246 offset:1024
	ds_read_b128 v[136:139], v246 offset:2048
	ds_read_b128 v[140:143], v246 offset:3072
	ds_read_b128 v[196:199], v248 offset:0
	ds_read_b128 v[162:165], v247 offset:0
	ds_read_b128 v[166:169], v247 offset:32
	ds_read_b128 v[170:173], v247 offset:64
	ds_read_b128 v[174:177], v247 offset:96
	s_waitcnt lgkmcnt(12)
	v_lshlrev_b32_e32 v229, 16, v213
	global_load_dwordx4 v[116:119], v235, s[32:33] offset:1024
	v_lshlrev_b32_e32 v228, 16, v212
	v_pk_add_f32 v[228:229], v[228:229], 0 op_sel_hi:[1,0]
	v_and_b32_e32 v231, 0xffff0000, v213
	v_and_b32_e32 v230, 0xffff0000, v212
	v_pk_add_f32 v[230:231], v[230:231], 0 op_sel_hi:[1,0]
	v_lshlrev_b32_e32 v49, 16, v215
	v_lshlrev_b32_e32 v48, 16, v214
	v_pk_add_f32 v[228:229], v[228:229], v[48:49]
	v_and_b32_e32 v215, 0xffff0000, v215
	v_and_b32_e32 v214, 0xffff0000, v214
	v_pk_add_f32 v[230:231], v[230:231], v[214:215]
	global_load_dwordx4 v[120:123], v235, s[32:33] offset:2048
	s_waitcnt lgkmcnt(11)
	v_lshlrev_b32_e32 v49, 16, v217
	v_lshlrev_b32_e32 v48, 16, v216
	v_pk_add_f32 v[228:229], v[228:229], v[48:49]
	v_and_b32_e32 v217, 0xffff0000, v217
	v_and_b32_e32 v216, 0xffff0000, v216
	v_pk_add_f32 v[230:231], v[230:231], v[216:217]
	v_lshlrev_b32_e32 v49, 16, v219
	v_lshlrev_b32_e32 v48, 16, v218
	v_pk_add_f32 v[228:229], v[228:229], v[48:49]
	global_load_dwordx4 v[124:127], v235, s[32:33] offset:3072
	v_and_b32_e32 v219, 0xffff0000, v219
	v_and_b32_e32 v218, 0xffff0000, v218
	v_pk_add_f32 v[230:231], v[230:231], v[218:219]
	s_waitcnt lgkmcnt(10)
	v_lshlrev_b32_e32 v49, 16, v221
	v_lshlrev_b32_e32 v48, 16, v220
	v_pk_add_f32 v[228:229], v[228:229], v[48:49]
	v_and_b32_e32 v221, 0xffff0000, v221
	v_and_b32_e32 v220, 0xffff0000, v220
	v_pk_add_f32 v[230:231], v[230:231], v[220:221]
	v_lshlrev_b32_e32 v49, 16, v223
	global_load_dwordx4 v[92:95], v232, s[34:35] offset:-4096
	v_lshlrev_b32_e32 v48, 16, v222
	v_pk_add_f32 v[228:229], v[228:229], v[48:49]
	v_and_b32_e32 v223, 0xffff0000, v223
	v_and_b32_e32 v222, 0xffff0000, v222
	v_pk_add_f32 v[230:231], v[230:231], v[222:223]
	s_waitcnt lgkmcnt(9)
	v_lshlrev_b32_e32 v49, 16, v225
	v_lshlrev_b32_e32 v48, 16, v224
	v_pk_add_f32 v[228:229], v[228:229], v[48:49]
	v_and_b32_e32 v225, 0xffff0000, v225
	v_and_b32_e32 v224, 0xffff0000, v224
	global_load_dwordx4 v[96:99], v232, s[34:35]
	v_pk_add_f32 v[230:231], v[230:231], v[224:225]
	v_lshlrev_b32_e32 v49, 16, v227
	v_lshlrev_b32_e32 v48, 16, v226
	v_pk_add_f32 v[228:229], v[228:229], v[48:49]
	v_and_b32_e32 v227, 0xffff0000, v227
	v_and_b32_e32 v226, 0xffff0000, v226
	v_pk_add_f32 v[230:231], v[230:231], v[226:227]
	v_cvt_pk_bf16_f32 v228, v228, v229
	v_cvt_pk_bf16_f32 v230, v230, v231
	global_store_dword v249, v228, s[38:39]
	global_load_dwordx4 v[100:103], v233, s[34:35] offset:-4096
	global_store_dword v250, v230, s[38:39]
	s_add_u32 s38, s38, s55
	s_addc_u32 s39, s39, s56
	v_cvt_pk_bf16_f32 v16, v16, v17
	v_cvt_pk_bf16_f32 v18, v18, v19
	v_cvt_pk_bf16_f32 v20, v20, v21
	v_cvt_pk_bf16_f32 v22, v22, v23
	v_cvt_pk_bf16_f32 v24, v24, v25
	v_cvt_pk_bf16_f32 v26, v26, v27
	v_cvt_pk_bf16_f32 v28, v28, v29
	v_cvt_pk_bf16_f32 v30, v30, v31
	global_load_dwordx4 v[104:107], v233, s[34:35]
	ds_write2st64_b32 v241, v16, v20 offset0:128 offset1:130
	ds_write2st64_b32 v242, v18, v22 offset0:129 offset1:131
	ds_write2st64_b32 v241, v24, v28 offset0:132 offset1:134
	ds_write2st64_b32 v242, v26, v30 offset0:133 offset1:135
	v_cvt_pk_bf16_f32 v32, v32, v33
	v_cvt_pk_bf16_f32 v34, v34, v35
	v_cvt_pk_bf16_f32 v36, v36, v37
	v_cvt_pk_bf16_f32 v38, v38, v39
	v_cvt_pk_bf16_f32 v40, v40, v41
	v_cvt_pk_bf16_f32 v42, v42, v43
	global_load_dwordx4 v[108:111], v251, s[36:37]
	v_cvt_pk_bf16_f32 v44, v44, v45
	v_cvt_pk_bf16_f32 v46, v46, v47
	ds_write2st64_b32 v243, v32, v36 offset0:128 offset1:130
	ds_write2st64_b32 v244, v34, v38 offset0:129 offset1:131
	ds_write2st64_b32 v243, v40, v44 offset0:132 offset1:134
	ds_write2st64_b32 v244, v42, v46 offset0:133 offset1:135
	s_add_u32 s32, s32, s53
	s_addc_u32 s33, s33, s56
	s_add_u32 s34, s34, s53
	s_addc_u32 s35, s35, s56
	s_add_u32 s36, s36, s54
	s_addc_u32 s37, s37, s56
	s_waitcnt lgkmcnt(0)
	s_barrier
; __device__ __forceinline__ void phase_scan(const Args& a, unsigned char* smem, int tid, int lane, int wave) {
;     ...
;         auto stepf = [&](const int step, unsigned& sc_issue, unsigned& sc_consume) __attribute__((always_inline)) {
;             const int nstep = step < 259 ? step + 1 : step, n2 = step < 258 ? step + 2 : 259;
;             SCAN_LOAD(nstep, nqe, nat);
;             SCAN_GLOAD(n2, gnxt);
;     ...
;             { int ss = step + SCOUT; ss = ss > 259 ? 259 : ss; const int gcs = SCAN_GC(ss); sc_issue = *(const unsigned*)(scb + (size_t)gcs * scsg); }
;     ...
;             const int gc = SCAN_GC(step); const size_t row0 = (size_t)gc * 64;
;             bf16x8 kdA[4];
;             { const bf16_t* kp = KDT + (((size_t)gc * 4 + h) * 8 + kb) * 2048 + lane * 8;
; #pragma unroll
;               for (int q = 0; q < 4; ++q) kdA[q] = *(const bf16x8*)(kp + 512 * q); }
;             const int rbuf = step & 1, nbuf = rbuf ^ 1;
;             if (gc < 512) {
;                 u32x4 s0, s1;
;                 s0.x = pk2(S[0], S[1]); s0.y = pk2(S[2], S[3]); s0.z = pk2(S[4], S[5]); s0.w = pk2(S[6], S[7]);
;                 s1.x = pk2(S[8], S[9]); s1.y = pk2(S[10], S[11]); s1.z = pk2(S[12], S[13]); s1.w = pk2(S[14], S[15]);
;                 const bf16x8 sb0 = __builtin_bit_cast(bf16x8, s0), sb1 = __builtin_bit_cast(bf16x8, s1);
;                 f32x16 o0, o1;
; #pragma unroll
;                 for (int i = 0; i < 16; ++i) { o0[i] = 0.f; o1[i] = 0.f; }
;                 o0 = mfma32(qeA[0], sb0, o0); o0 = mfma32(qeA[1], sb1, o0);
;                 o1 = mfma32(qeA[2], sb0, o1); o1 = mfma32(qeA[3], sb1, o1);
;                 const int w3 = wave & 3;
;                 const bf16x8 vs = w3 == 0 ? vB[0] : (w3 == 1 ? vB[1] : (w3 == 2 ? vB[2] : vB[3]));
;                 if (wave < 4) o0 = mfma32(atA, vs, o0); else o1 = mfma32(atA, vs, o1);
;                 unsigned* rb = red + (size_t)(rbuf * 8 + wave) * 1024 + lane; unsigned* rbx = red + (size_t)(rbuf * 8 + wave) * 1024 + (lane ^ 32);
; #pragma unroll
;                 for (int i = 0; i < 8; ++i) { unsigned* w_ = (i & 1) ? rbx : rb; w_[i * 64] = pk2(o0[2 * i], o0[2 * i + 1]); w_[512 + i * 64] = pk2(o1[2 * i], o1[2 * i + 1]); }
;             }
;             SCAN_GSTORE(nbuf, gcur);
;             __syncthreads();
;             if (gc < 512) {
	s_waitcnt vmcnt(12)
	ds_write_b128 v239, v[204:207]
	global_load_dwordx4 v[204:207], v[194:195], off
	v_lshl_add_u64 v[194:195], v[194:195], 0, v[254:255]
	v_cvt_pk_bf16_f32 v48, v0, v1
	v_cvt_pk_bf16_f32 v49, v2, v3
	v_cvt_pk_bf16_f32 v50, v4, v5
	v_cvt_pk_bf16_f32 v51, v6, v7
	v_cvt_pk_bf16_f32 v52, v8, v9
	v_cvt_pk_bf16_f32 v53, v10, v11
	v_cvt_pk_bf16_f32 v54, v12, v13
	v_cvt_pk_bf16_f32 v55, v14, v15
	v_mfma_f32_32x32x16_bf16 v[16:31], v[56:59], v[48:51], 0
	v_pk_mul_f32 v[0:1], v[162:163], v[0:1]
	v_pk_mul_f32 v[2:3], v[164:165], v[2:3]
	v_pk_mul_f32 v[4:5], v[166:167], v[4:5]
	v_mfma_f32_32x32x16_bf16 v[32:47], v[64:67], v[48:51], 0
	v_pk_mul_f32 v[6:7], v[168:169], v[6:7]
	v_pk_mul_f32 v[8:9], v[170:171], v[8:9]
	v_pk_mul_f32 v[10:11], v[172:173], v[10:11]
	v_mfma_f32_32x32x16_bf16 v[16:31], v[60:63], v[52:55], v[16:31]
	v_pk_mul_f32 v[12:13], v[174:175], v[12:13]
	v_pk_mul_f32 v[14:15], v[176:177], v[14:15]
	v_mfma_f32_32x32x16_bf16 v[32:47], v[68:71], v[52:55], v[32:47]
	v_mfma_f32_32x32x16_bf16 v[16:31], v[72:75], v[196:199], v[16:31]
	v_mfma_f32_32x32x16_bf16 v[0:15], v[76:79], v[128:131], v[0:15]
	v_mfma_f32_32x32x16_bf16 v[0:15], v[80:83], v[132:135], v[0:15]
	v_mfma_f32_32x32x16_bf16 v[0:15], v[84:87], v[136:139], v[0:15]
	v_mfma_f32_32x32x16_bf16 v[0:15], v[88:91], v[140:143], v[0:15]
	ds_read2st64_b64 v[212:215], v245 offset0:64 offset1:72
	ds_read2st64_b64 v[216:219], v245 offset0:80 offset1:88
	ds_read2st64_b64 v[220:223], v245 offset0:96 offset1:104
	ds_read2st64_b64 v[224:227], v245 offset0:112 offset1:120
	ds_read_b128 v[144:147], v246 offset:4096
	global_load_dwordx4 v[76:79], v235, s[32:33]
	ds_read_b128 v[148:151], v246 offset:5120
	ds_read_b128 v[152:155], v246 offset:6144
	ds_read_b128 v[156:159], v246 offset:7168
	ds_read_b128 v[200:203], v248 offset:4096
	ds_read_b128 v[178:181], v247 offset:1024
	ds_read_b128 v[182:185], v247 offset:1056
	ds_read_b128 v[186:189], v247 offset:1088
	ds_read_b128 v[190:193], v247 offset:1120
	s_waitcnt lgkmcnt(12)
	v_lshlrev_b32_e32 v229, 16, v213
	global_load_dwordx4 v[80:83], v235, s[32:33] offset:1024
	v_lshlrev_b32_e32 v228, 16, v212
	v_pk_add_f32 v[228:229], v[228:229], 0 op_sel_hi:[1,0]
	v_and_b32_e32 v231, 0xffff0000, v213
	v_and_b32_e32 v230, 0xffff0000, v212
	v_pk_add_f32 v[230:231], v[230:231], 0 op_sel_hi:[1,0]
	v_lshlrev_b32_e32 v49, 16, v215
	v_lshlrev_b32_e32 v48, 16, v214
	v_pk_add_f32 v[228:229], v[228:229], v[48:49]
	v_and_b32_e32 v215, 0xffff0000, v215
	v_and_b32_e32 v214, 0xffff0000, v214
	v_pk_add_f32 v[230:231], v[230:231], v[214:215]
	global_load_dwordx4 v[84:87], v235, s[32:33] offset:2048
	s_waitcnt lgkmcnt(11)
	v_lshlrev_b32_e32 v49, 16, v217
	v_lshlrev_b32_e32 v48, 16, v216
	v_pk_add_f32 v[228:229], v[228:229], v[48:49]
	v_and_b32_e32 v217, 0xffff0000, v217
	v_and_b32_e32 v216, 0xffff0000, v216
	v_pk_add_f32 v[230:231], v[230:231], v[216:217]
	v_lshlrev_b32_e32 v49, 16, v219
	v_lshlrev_b32_e32 v48, 16, v218
	v_pk_add_f32 v[228:229], v[228:229], v[48:49]
	global_load_dwordx4 v[88:91], v235, s[32:33] offset:3072
	v_and_b32_e32 v219, 0xffff0000, v219
	v_and_b32_e32 v218, 0xffff0000, v218
	v_pk_add_f32 v[230:231], v[230:231], v[218:219]
	s_waitcnt lgkmcnt(10)
	v_lshlrev_b32_e32 v49, 16, v221
	v_lshlrev_b32_e32 v48, 16, v220
	v_pk_add_f32 v[228:229], v[228:229], v[48:49]
	v_and_b32_e32 v221, 0xffff0000, v221
	v_and_b32_e32 v220, 0xffff0000, v220
	v_pk_add_f32 v[230:231], v[230:231], v[220:221]
	v_lshlrev_b32_e32 v49, 16, v223
	global_load_dwordx4 v[56:59], v232, s[34:35] offset:-4096
	v_lshlrev_b32_e32 v48, 16, v222
	v_pk_add_f32 v[228:229], v[228:229], v[48:49]
	v_and_b32_e32 v223, 0xffff0000, v223
	v_and_b32_e32 v222, 0xffff0000, v222
	v_pk_add_f32 v[230:231], v[230:231], v[222:223]
	s_waitcnt lgkmcnt(9)
	v_lshlrev_b32_e32 v49, 16, v225
	v_lshlrev_b32_e32 v48, 16, v224
	v_pk_add_f32 v[228:229], v[228:229], v[48:49]
	v_and_b32_e32 v225, 0xffff0000, v225
	v_and_b32_e32 v224, 0xffff0000, v224
	global_load_dwordx4 v[60:63], v232, s[34:35]
	v_pk_add_f32 v[230:231], v[230:231], v[224:225]
	v_lshlrev_b32_e32 v49, 16, v227
	v_lshlrev_b32_e32 v48, 16, v226
	v_pk_add_f32 v[228:229], v[228:229], v[48:49]
	v_and_b32_e32 v227, 0xffff0000, v227
	v_and_b32_e32 v226, 0xffff0000, v226
	v_pk_add_f32 v[230:231], v[230:231], v[226:227]
	v_cvt_pk_bf16_f32 v228, v228, v229
	v_cvt_pk_bf16_f32 v230, v230, v231
	global_store_dword v249, v228, s[38:39]
	global_load_dwordx4 v[64:67], v233, s[34:35] offset:-4096
	global_store_dword v250, v230, s[38:39]
	s_add_u32 s38, s38, s55
	s_addc_u32 s39, s39, s56
	v_cvt_pk_bf16_f32 v16, v16, v17
	v_cvt_pk_bf16_f32 v18, v18, v19
	v_cvt_pk_bf16_f32 v20, v20, v21
	v_cvt_pk_bf16_f32 v22, v22, v23
	v_cvt_pk_bf16_f32 v24, v24, v25
	v_cvt_pk_bf16_f32 v26, v26, v27
	v_cvt_pk_bf16_f32 v28, v28, v29
	v_cvt_pk_bf16_f32 v30, v30, v31
	global_load_dwordx4 v[68:71], v233, s[34:35]
	ds_write2st64_b32 v241, v16, v20 offset0:0 offset1:2
	ds_write2st64_b32 v242, v18, v22 offset0:1 offset1:3
	ds_write2st64_b32 v241, v24, v28 offset0:4 offset1:6
	ds_write2st64_b32 v242, v26, v30 offset0:5 offset1:7
	v_cvt_pk_bf16_f32 v32, v32, v33
	v_cvt_pk_bf16_f32 v34, v34, v35
	v_cvt_pk_bf16_f32 v36, v36, v37
	v_cvt_pk_bf16_f32 v38, v38, v39
	v_cvt_pk_bf16_f32 v40, v40, v41
	v_cvt_pk_bf16_f32 v42, v42, v43
	global_load_dwordx4 v[72:75], v251, s[36:37]
	v_cvt_pk_bf16_f32 v44, v44, v45
	v_cvt_pk_bf16_f32 v46, v46, v47
	ds_write2st64_b32 v243, v32, v36 offset0:0 offset1:2
	ds_write2st64_b32 v244, v34, v38 offset0:1 offset1:3
	ds_write2st64_b32 v243, v40, v44 offset0:4 offset1:6
	ds_write2st64_b32 v244, v42, v46 offset0:5 offset1:7
	s_add_u32 s32, s32, s53
	s_addc_u32 s33, s33, s56
	s_add_u32 s34, s34, s53
	s_addc_u32 s35, s35, s56
	s_add_u32 s36, s36, s54
	s_addc_u32 s37, s37, s56
	s_waitcnt lgkmcnt(0)
	s_barrier
; __device__ __forceinline__ void phase_scan(const Args& a, unsigned char* smem, int tid, int lane, int wave) {
;     ...
;         auto stepf = [&](const int step, unsigned& sc_issue, unsigned& sc_consume) __attribute__((always_inline)) {
;             const int nstep = step < 259 ? step + 1 : step, n2 = step < 258 ? step + 2 : 259;
;             SCAN_LOAD(nstep, nqe, nat);
;             SCAN_GLOAD(n2, gnxt);
;     ...
;             { int ss = step + SCOUT; ss = ss > 259 ? 259 : ss; const int gcs = SCAN_GC(ss); sc_issue = *(const unsigned*)(scb + (size_t)gcs * scsg); }
;     ...
;             const int gc = SCAN_GC(step); const size_t row0 = (size_t)gc * 64;
;             bf16x8 kdA[4];
;             { const bf16_t* kp = KDT + (((size_t)gc * 4 + h) * 8 + kb) * 2048 + lane * 8;
; #pragma unroll
;               for (int q = 0; q < 4; ++q) kdA[q] = *(const bf16x8*)(kp + 512 * q); }
;             const int rbuf = step & 1, nbuf = rbuf ^ 1;
;             if (gc < 512) {
;                 u32x4 s0, s1;
;                 s0.x = pk2(S[0], S[1]); s0.y = pk2(S[2], S[3]); s0.z = pk2(S[4], S[5]); s0.w = pk2(S[6], S[7]);
;                 s1.x = pk2(S[8], S[9]); s1.y = pk2(S[10], S[11]); s1.z = pk2(S[12], S[13]); s1.w = pk2(S[14], S[15]);
;                 const bf16x8 sb0 = __builtin_bit_cast(bf16x8, s0), sb1 = __builtin_bit_cast(bf16x8, s1);
;                 f32x16 o0, o1;
; #pragma unroll
;                 for (int i = 0; i < 16; ++i) { o0[i] = 0.f; o1[i] = 0.f; }
;                 o0 = mfma32(qeA[0], sb0, o0); o0 = mfma32(qeA[1], sb1, o0);
;                 o1 = mfma32(qeA[2], sb0, o1); o1 = mfma32(qeA[3], sb1, o1);
;                 const int w3 = wave & 3;
;                 const bf16x8 vs = w3 == 0 ? vB[0] : (w3 == 1 ? vB[1] : (w3 == 2 ? vB[2] : vB[3]));
;                 if (wave < 4) o0 = mfma32(atA, vs, o0); else o1 = mfma32(atA, vs, o1);
;                 unsigned* rb = red + (size_t)(rbuf * 8 + wave) * 1024 + lane; unsigned* rbx = red + (size_t)(rbuf * 8 + wave) * 1024 + (lane ^ 32);
; #pragma unroll
;                 for (int i = 0; i < 8; ++i) { unsigned* w_ = (i & 1) ? rbx : rb; w_[i * 64] = pk2(o0[2 * i], o0[2 * i + 1]); w_[512 + i * 64] = pk2(o1[2 * i], o1[2 * i + 1]); }
;             }
;             SCAN_GSTORE(nbuf, gcur);
;             __syncthreads();
;             if (gc < 512) {
	s_waitcnt vmcnt(12)
	ds_write_b128 v240, v[208:211]
	global_load_dwordx4 v[208:211], v[194:195], off
	v_lshl_add_u64 v[194:195], v[194:195], 0, v[254:255]
	v_cvt_pk_bf16_f32 v48, v0, v1
	v_cvt_pk_bf16_f32 v49, v2, v3
	v_cvt_pk_bf16_f32 v50, v4, v5
	v_cvt_pk_bf16_f32 v51, v6, v7
	v_cvt_pk_bf16_f32 v52, v8, v9
	v_cvt_pk_bf16_f32 v53, v10, v11
	v_cvt_pk_bf16_f32 v54, v12, v13
	v_cvt_pk_bf16_f32 v55, v14, v15
	v_mfma_f32_32x32x16_bf16 v[16:31], v[92:95], v[48:51], 0
	v_pk_mul_f32 v[0:1], v[178:179], v[0:1]
	v_pk_mul_f32 v[2:3], v[180:181], v[2:3]
	v_pk_mul_f32 v[4:5], v[182:183], v[4:5]
	v_mfma_f32_32x32x16_bf16 v[32:47], v[100:103], v[48:51], 0
	v_pk_mul_f32 v[6:7], v[184:185], v[6:7]
	v_pk_mul_f32 v[8:9], v[186:187], v[8:9]
	v_pk_mul_f32 v[10:11], v[188:189], v[10:11]
	v_mfma_f32_32x32x16_bf16 v[16:31], v[96:99], v[52:55], v[16:31]
	v_pk_mul_f32 v[12:13], v[190:191], v[12:13]
	v_pk_mul_f32 v[14:15], v[192:193], v[14:15]
	v_mfma_f32_32x32x16_bf16 v[32:47], v[104:107], v[52:55], v[32:47]
	v_mfma_f32_32x32x16_bf16 v[16:31], v[108:111], v[200:203], v[16:31]
	v_mfma_f32_32x32x16_bf16 v[0:15], v[112:115], v[144:147], v[0:15]
	v_mfma_f32_32x32x16_bf16 v[0:15], v[116:119], v[148:151], v[0:15]
	v_mfma_f32_32x32x16_bf16 v[0:15], v[120:123], v[152:155], v[0:15]
	v_mfma_f32_32x32x16_bf16 v[0:15], v[124:127], v[156:159], v[0:15]
	ds_read2st64_b64 v[212:215], v245 offset0:0 offset1:8
	ds_read2st64_b64 v[216:219], v245 offset0:16 offset1:24
	ds_read2st64_b64 v[220:223], v245 offset0:32 offset1:40
	ds_read2st64_b64 v[224:227], v245 offset0:48 offset1:56
	ds_read_b128 v[128:131], v246 offset:0
	global_load_dwordx4 v[112:115], v235, s[32:33]
	ds_read_b128 v[132:135], v246 offset:1024
	ds_read_b128 v[136:139], v246 offset:2048
	ds_read_b128 v[140:143], v246 offset:3072
	ds_read_b128 v[196:199], v248 offset:0
	ds_read_b128 v[162:165], v247 offset:0
	ds_read_b128 v[166:169], v247 offset:32
	ds_read_b128 v[170:173], v247 offset:64
	ds_read_b128 v[174:177], v247 offset:96
	s_waitcnt lgkmcnt(12)
	v_lshlrev_b32_e32 v229, 16, v213
	global_load_dwordx4 v[116:119], v235, s[32:33] offset:1024
	v_lshlrev_b32_e32 v228, 16, v212
	v_pk_add_f32 v[228:229], v[228:229], 0 op_sel_hi:[1,0]
	v_and_b32_e32 v231, 0xffff0000, v213
	v_and_b32_e32 v230, 0xffff0000, v212
	v_pk_add_f32 v[230:231], v[230:231], 0 op_sel_hi:[1,0]
	v_lshlrev_b32_e32 v49, 16, v215
	v_lshlrev_b32_e32 v48, 16, v214
	v_pk_add_f32 v[228:229], v[228:229], v[48:49]
	v_and_b32_e32 v215, 0xffff0000, v215
	v_and_b32_e32 v214, 0xffff0000, v214
	v_pk_add_f32 v[230:231], v[230:231], v[214:215]
	global_load_dwordx4 v[120:123], v235, s[32:33] offset:2048
	s_waitcnt lgkmcnt(11)
	v_lshlrev_b32_e32 v49, 16, v217
	v_lshlrev_b32_e32 v48, 16, v216
	v_pk_add_f32 v[228:229], v[228:229], v[48:49]
	v_and_b32_e32 v217, 0xffff0000, v217
	v_and_b32_e32 v216, 0xffff0000, v216
	v_pk_add_f32 v[230:231], v[230:231], v[216:217]
	v_lshlrev_b32_e32 v49, 16, v219
	v_lshlrev_b32_e32 v48, 16, v218
	v_pk_add_f32 v[228:229], v[228:229], v[48:49]
	global_load_dwordx4 v[124:127], v235, s[32:33] offset:3072
	v_and_b32_e32 v219, 0xffff0000, v219
	v_and_b32_e32 v218, 0xffff0000, v218
	v_pk_add_f32 v[230:231], v[230:231], v[218:219]
	s_waitcnt lgkmcnt(10)
	v_lshlrev_b32_e32 v49, 16, v221
	v_lshlrev_b32_e32 v48, 16, v220
	v_pk_add_f32 v[228:229], v[228:229], v[48:49]
	v_and_b32_e32 v221, 0xffff0000, v221
	v_and_b32_e32 v220, 0xffff0000, v220
	v_pk_add_f32 v[230:231], v[230:231], v[220:221]
	v_lshlrev_b32_e32 v49, 16, v223
	global_load_dwordx4 v[92:95], v232, s[34:35] offset:-4096
	v_lshlrev_b32_e32 v48, 16, v222
	v_pk_add_f32 v[228:229], v[228:229], v[48:49]
	v_and_b32_e32 v223, 0xffff0000, v223
	v_and_b32_e32 v222, 0xffff0000, v222
	v_pk_add_f32 v[230:231], v[230:231], v[222:223]
	s_waitcnt lgkmcnt(9)
	v_lshlrev_b32_e32 v49, 16, v225
	v_lshlrev_b32_e32 v48, 16, v224
	v_pk_add_f32 v[228:229], v[228:229], v[48:49]
	v_and_b32_e32 v225, 0xffff0000, v225
	v_and_b32_e32 v224, 0xffff0000, v224
	global_load_dwordx4 v[96:99], v232, s[34:35]
	v_pk_add_f32 v[230:231], v[230:231], v[224:225]
	v_lshlrev_b32_e32 v49, 16, v227
	v_lshlrev_b32_e32 v48, 16, v226
	v_pk_add_f32 v[228:229], v[228:229], v[48:49]
	v_and_b32_e32 v227, 0xffff0000, v227
	v_and_b32_e32 v226, 0xffff0000, v226
	v_pk_add_f32 v[230:231], v[230:231], v[226:227]
	v_cvt_pk_bf16_f32 v228, v228, v229
	v_cvt_pk_bf16_f32 v230, v230, v231
	global_store_dword v249, v228, s[38:39]
	global_load_dwordx4 v[100:103], v233, s[34:35] offset:-4096
	global_store_dword v250, v230, s[38:39]
	s_add_u32 s38, s38, s55
	s_addc_u32 s39, s39, s56
	v_cvt_pk_bf16_f32 v16, v16, v17
	v_cvt_pk_bf16_f32 v18, v18, v19
	v_cvt_pk_bf16_f32 v20, v20, v21
	v_cvt_pk_bf16_f32 v22, v22, v23
	v_cvt_pk_bf16_f32 v24, v24, v25
	v_cvt_pk_bf16_f32 v26, v26, v27
	v_cvt_pk_bf16_f32 v28, v28, v29
	v_cvt_pk_bf16_f32 v30, v30, v31
	global_load_dwordx4 v[104:107], v233, s[34:35]
	ds_write2st64_b32 v241, v16, v20 offset0:128 offset1:130
	ds_write2st64_b32 v242, v18, v22 offset0:129 offset1:131
	ds_write2st64_b32 v241, v24, v28 offset0:132 offset1:134
	ds_write2st64_b32 v242, v26, v30 offset0:133 offset1:135
	v_cvt_pk_bf16_f32 v32, v32, v33
	v_cvt_pk_bf16_f32 v34, v34, v35
	v_cvt_pk_bf16_f32 v36, v36, v37
	v_cvt_pk_bf16_f32 v38, v38, v39
	v_cvt_pk_bf16_f32 v40, v40, v41
	v_cvt_pk_bf16_f32 v42, v42, v43
	global_load_dwordx4 v[108:111], v251, s[36:37]
	v_cvt_pk_bf16_f32 v44, v44, v45
	v_cvt_pk_bf16_f32 v46, v46, v47
	ds_write2st64_b32 v243, v32, v36 offset0:128 offset1:130
	ds_write2st64_b32 v244, v34, v38 offset0:129 offset1:131
	ds_write2st64_b32 v243, v40, v44 offset0:132 offset1:134
	ds_write2st64_b32 v244, v42, v46 offset0:133 offset1:135
	s_add_u32 s32, s32, s53
	s_addc_u32 s33, s33, s56
	s_add_u32 s34, s34, s53
	s_addc_u32 s35, s35, s56
	s_add_u32 s36, s36, s54
	s_addc_u32 s37, s37, s56
	s_waitcnt lgkmcnt(0)
	s_barrier
	s_mov_b32 s30, 4
; __device__ __forceinline__ void phase_scan(const Args& a, unsigned char* smem, int tid, int lane, int wave) {
;     ...
;         auto stepf = [&](const int step, unsigned& sc_issue, unsigned& sc_consume) __attribute__((always_inline)) {
;             const int nstep = step < 259 ? step + 1 : step, n2 = step < 258 ? step + 2 : 259;
;             SCAN_LOAD(nstep, nqe, nat);
;             SCAN_GLOAD(n2, gnxt);
;     ...
;             { int ss = step + SCOUT; ss = ss > 259 ? 259 : ss; const int gcs = SCAN_GC(ss); sc_issue = *(const unsigned*)(scb + (size_t)gcs * scsg); }
;     ...
;             const int gc = SCAN_GC(step); const size_t row0 = (size_t)gc * 64;
;             bf16x8 kdA[4];
;             { const bf16_t* kp = KDT + (((size_t)gc * 4 + h) * 8 + kb) * 2048 + lane * 8;
; #pragma unroll
;               for (int q = 0; q < 4; ++q) kdA[q] = *(const bf16x8*)(kp + 512 * q); }
;             const int rbuf = step & 1, nbuf = rbuf ^ 1;
;             if (gc < 512) {
;                 u32x4 s0, s1;
;                 s0.x = pk2(S[0], S[1]); s0.y = pk2(S[2], S[3]); s0.z = pk2(S[4], S[5]); s0.w = pk2(S[6], S[7]);
;                 s1.x = pk2(S[8], S[9]); s1.y = pk2(S[10], S[11]); s1.z = pk2(S[12], S[13]); s1.w = pk2(S[14], S[15]);
;                 const bf16x8 sb0 = __builtin_bit_cast(bf16x8, s0), sb1 = __builtin_bit_cast(bf16x8, s1);
;                 f32x16 o0, o1;
; #pragma unroll
;                 for (int i = 0; i < 16; ++i) { o0[i] = 0.f; o1[i] = 0.f; }
;                 o0 = mfma32(qeA[0], sb0, o0); o0 = mfma32(qeA[1], sb1, o0);
;                 o1 = mfma32(qeA[2], sb0, o1); o1 = mfma32(qeA[3], sb1, o1);
;                 const int w3 = wave & 3;
;                 const bf16x8 vs = w3 == 0 ? vB[0] : (w3 == 1 ? vB[1] : (w3 == 2 ? vB[2] : vB[3]));
;                 if (wave < 4) o0 = mfma32(atA, vs, o0); else o1 = mfma32(atA, vs, o1);
;                 unsigned* rb = red + (size_t)(rbuf * 8 + wave) * 1024 + lane; unsigned* rbx = red + (size_t)(rbuf * 8 + wave) * 1024 + (lane ^ 32);
; #pragma unroll
;                 for (int i = 0; i < 8; ++i) { unsigned* w_ = (i & 1) ? rbx : rb; w_[i * 64] = pk2(o0[2 * i], o0[2 * i + 1]); w_[512 + i * 64] = pk2(o1[2 * i], o1[2 * i + 1]); }
;             }
;             SCAN_GSTORE(nbuf, gcur);
;             __syncthreads();
;             if (gc < 512) {
.Lscan_loopA:
	s_waitcnt vmcnt(12)
	ds_write_b128 v239, v[204:207]
	global_load_dwordx4 v[204:207], v[194:195], off
	v_lshl_add_u64 v[194:195], v[194:195], 0, v[254:255]
	v_cvt_pk_bf16_f32 v48, v0, v1
	v_cvt_pk_bf16_f32 v49, v2, v3
	v_cvt_pk_bf16_f32 v50, v4, v5
	v_cvt_pk_bf16_f32 v51, v6, v7
	v_cvt_pk_bf16_f32 v52, v8, v9
	v_cvt_pk_bf16_f32 v53, v10, v11
	v_cvt_pk_bf16_f32 v54, v12, v13
	v_cvt_pk_bf16_f32 v55, v14, v15
	v_mfma_f32_32x32x16_bf16 v[16:31], v[56:59], v[48:51], 0
	v_pk_mul_f32 v[0:1], v[162:163], v[0:1]
	v_pk_mul_f32 v[2:3], v[164:165], v[2:3]
	v_pk_mul_f32 v[4:5], v[166:167], v[4:5]
	v_mfma_f32_32x32x16_bf16 v[32:47], v[64:67], v[48:51], 0
	v_pk_mul_f32 v[6:7], v[168:169], v[6:7]
	v_pk_mul_f32 v[8:9], v[170:171], v[8:9]
	v_pk_mul_f32 v[10:11], v[172:173], v[10:11]
	v_mfma_f32_32x32x16_bf16 v[16:31], v[60:63], v[52:55], v[16:31]
	v_pk_mul_f32 v[12:13], v[174:175], v[12:13]
	v_pk_mul_f32 v[14:15], v[176:177], v[14:15]
	v_mfma_f32_32x32x16_bf16 v[32:47], v[68:71], v[52:55], v[32:47]
	v_mfma_f32_32x32x16_bf16 v[16:31], v[72:75], v[196:199], v[16:31]
	v_mfma_f32_32x32x16_bf16 v[0:15], v[76:79], v[128:131], v[0:15]
	v_mfma_f32_32x32x16_bf16 v[0:15], v[80:83], v[132:135], v[0:15]
	v_mfma_f32_32x32x16_bf16 v[0:15], v[84:87], v[136:139], v[0:15]
	v_mfma_f32_32x32x16_bf16 v[0:15], v[88:91], v[140:143], v[0:15]
	ds_read2st64_b64 v[212:215], v245 offset0:64 offset1:72
	ds_read2st64_b64 v[216:219], v245 offset0:80 offset1:88
	ds_read2st64_b64 v[220:223], v245 offset0:96 offset1:104
	ds_read2st64_b64 v[224:227], v245 offset0:112 offset1:120
	ds_read_b128 v[144:147], v246 offset:4096
	global_load_dwordx4 v[76:79], v235, s[32:33]
	ds_read_b128 v[148:151], v246 offset:5120
	ds_read_b128 v[152:155], v246 offset:6144
	ds_read_b128 v[156:159], v246 offset:7168
	ds_read_b128 v[200:203], v248 offset:4096
	ds_read_b128 v[178:181], v247 offset:1024
	ds_read_b128 v[182:185], v247 offset:1056
	ds_read_b128 v[186:189], v247 offset:1088
	ds_read_b128 v[190:193], v247 offset:1120
	s_waitcnt lgkmcnt(12)
	v_lshlrev_b32_e32 v229, 16, v213
	global_load_dwordx4 v[80:83], v235, s[32:33] offset:1024
	v_lshlrev_b32_e32 v228, 16, v212
	v_pk_add_f32 v[228:229], v[228:229], 0 op_sel_hi:[1,0]
	v_and_b32_e32 v231, 0xffff0000, v213
	v_and_b32_e32 v230, 0xffff0000, v212
	v_pk_add_f32 v[230:231], v[230:231], 0 op_sel_hi:[1,0]
	v_lshlrev_b32_e32 v49, 16, v215
	v_lshlrev_b32_e32 v48, 16, v214
	v_pk_add_f32 v[228:229], v[228:229], v[48:49]
	v_and_b32_e32 v215, 0xffff0000, v215
	v_and_b32_e32 v214, 0xffff0000, v214
	v_pk_add_f32 v[230:231], v[230:231], v[214:215]
	global_load_dwordx4 v[84:87], v235, s[32:33] offset:2048
	s_waitcnt lgkmcnt(11)
	v_lshlrev_b32_e32 v49, 16, v217
	v_lshlrev_b32_e32 v48, 16, v216
	v_pk_add_f32 v[228:229], v[228:229], v[48:49]
	v_and_b32_e32 v217, 0xffff0000, v217
	v_and_b32_e32 v216, 0xffff0000, v216
	v_pk_add_f32 v[230:231], v[230:231], v[216:217]
	v_lshlrev_b32_e32 v49, 16, v219
	v_lshlrev_b32_e32 v48, 16, v218
	v_pk_add_f32 v[228:229], v[228:229], v[48:49]
	global_load_dwordx4 v[88:91], v235, s[32:33] offset:3072
	v_and_b32_e32 v219, 0xffff0000, v219
	v_and_b32_e32 v218, 0xffff0000, v218
	v_pk_add_f32 v[230:231], v[230:231], v[218:219]
	s_waitcnt lgkmcnt(10)
	v_lshlrev_b32_e32 v49, 16, v221
	v_lshlrev_b32_e32 v48, 16, v220
	v_pk_add_f32 v[228:229], v[228:229], v[48:49]
	v_and_b32_e32 v221, 0xffff0000, v221
	v_and_b32_e32 v220, 0xffff0000, v220
	v_pk_add_f32 v[230:231], v[230:231], v[220:221]
	v_lshlrev_b32_e32 v49, 16, v223
	global_load_dwordx4 v[56:59], v232, s[34:35] offset:-4096
	v_lshlrev_b32_e32 v48, 16, v222
	v_pk_add_f32 v[228:229], v[228:229], v[48:49]
	v_and_b32_e32 v223, 0xffff0000, v223
	v_and_b32_e32 v222, 0xffff0000, v222
	v_pk_add_f32 v[230:231], v[230:231], v[222:223]
	s_waitcnt lgkmcnt(9)
	v_lshlrev_b32_e32 v49, 16, v225
	v_lshlrev_b32_e32 v48, 16, v224
	v_pk_add_f32 v[228:229], v[228:229], v[48:49]
	v_and_b32_e32 v225, 0xffff0000, v225
	v_and_b32_e32 v224, 0xffff0000, v224
	global_load_dwordx4 v[60:63], v232, s[34:35]
	v_pk_add_f32 v[230:231], v[230:231], v[224:225]
	v_lshlrev_b32_e32 v49, 16, v227
	v_lshlrev_b32_e32 v48, 16, v226
	v_pk_add_f32 v[228:229], v[228:229], v[48:49]
	v_and_b32_e32 v227, 0xffff0000, v227
	v_and_b32_e32 v226, 0xffff0000, v226
	v_pk_add_f32 v[230:231], v[230:231], v[226:227]
	v_cvt_pk_bf16_f32 v228, v228, v229
	v_cvt_pk_bf16_f32 v230, v230, v231
	global_store_dword v249, v228, s[38:39]
	global_load_dwordx4 v[64:67], v233, s[34:35] offset:-4096
	global_store_dword v250, v230, s[38:39]
	s_add_u32 s38, s38, s55
	s_addc_u32 s39, s39, s56
	v_cvt_pk_bf16_f32 v16, v16, v17
	v_cvt_pk_bf16_f32 v18, v18, v19
	v_cvt_pk_bf16_f32 v20, v20, v21
	v_cvt_pk_bf16_f32 v22, v22, v23
	v_cvt_pk_bf16_f32 v24, v24, v25
	v_cvt_pk_bf16_f32 v26, v26, v27
	v_cvt_pk_bf16_f32 v28, v28, v29
	v_cvt_pk_bf16_f32 v30, v30, v31
	global_load_dwordx4 v[68:71], v233, s[34:35]
	ds_write2st64_b32 v241, v16, v20 offset0:0 offset1:2
	ds_write2st64_b32 v242, v18, v22 offset0:1 offset1:3
	ds_write2st64_b32 v241, v24, v28 offset0:4 offset1:6
	ds_write2st64_b32 v242, v26, v30 offset0:5 offset1:7
	v_cvt_pk_bf16_f32 v32, v32, v33
	v_cvt_pk_bf16_f32 v34, v34, v35
	v_cvt_pk_bf16_f32 v36, v36, v37
	v_cvt_pk_bf16_f32 v38, v38, v39
	v_cvt_pk_bf16_f32 v40, v40, v41
	v_cvt_pk_bf16_f32 v42, v42, v43
	global_load_dwordx4 v[72:75], v251, s[36:37]
	v_cvt_pk_bf16_f32 v44, v44, v45
	v_cvt_pk_bf16_f32 v46, v46, v47
	ds_write2st64_b32 v243, v32, v36 offset0:0 offset1:2
	ds_write2st64_b32 v244, v34, v38 offset0:1 offset1:3
	ds_write2st64_b32 v243, v40, v44 offset0:4 offset1:6
	ds_write2st64_b32 v244, v42, v46 offset0:5 offset1:7
	s_add_u32 s32, s32, s53
	s_addc_u32 s33, s33, s56
	s_add_u32 s34, s34, s53
	s_addc_u32 s35, s35, s56
	s_add_u32 s36, s36, s54
	s_addc_u32 s37, s37, s56
	s_waitcnt lgkmcnt(0)
	s_barrier
; __device__ __forceinline__ void phase_scan(const Args& a, unsigned char* smem, int tid, int lane, int wave) {
;     ...
;         auto stepf = [&](const int step, unsigned& sc_issue, unsigned& sc_consume) __attribute__((always_inline)) {
;             const int nstep = step < 259 ? step + 1 : step, n2 = step < 258 ? step + 2 : 259;
;             SCAN_LOAD(nstep, nqe, nat);
;             SCAN_GLOAD(n2, gnxt);
;     ...
;             { int ss = step + SCOUT; ss = ss > 259 ? 259 : ss; const int gcs = SCAN_GC(ss); sc_issue = *(const unsigned*)(scb + (size_t)gcs * scsg); }
;     ...
;             const int gc = SCAN_GC(step); const size_t row0 = (size_t)gc * 64;
;             bf16x8 kdA[4];
;             { const bf16_t* kp = KDT + (((size_t)gc * 4 + h) * 8 + kb) * 2048 + lane * 8;
; #pragma unroll
;               for (int q = 0; q < 4; ++q) kdA[q] = *(const bf16x8*)(kp + 512 * q); }
;             const int rbuf = step & 1, nbuf = rbuf ^ 1;
;             if (gc < 512) {
;                 u32x4 s0, s1;
;                 s0.x = pk2(S[0], S[1]); s0.y = pk2(S[2], S[3]); s0.z = pk2(S[4], S[5]); s0.w = pk2(S[6], S[7]);
;                 s1.x = pk2(S[8], S[9]); s1.y = pk2(S[10], S[11]); s1.z = pk2(S[12], S[13]); s1.w = pk2(S[14], S[15]);
;                 const bf16x8 sb0 = __builtin_bit_cast(bf16x8, s0), sb1 = __builtin_bit_cast(bf16x8, s1);
;                 f32x16 o0, o1;
; #pragma unroll
;                 for (int i = 0; i < 16; ++i) { o0[i] = 0.f; o1[i] = 0.f; }
;                 o0 = mfma32(qeA[0], sb0, o0); o0 = mfma32(qeA[1], sb1, o0);
;                 o1 = mfma32(qeA[2], sb0, o1); o1 = mfma32(qeA[3], sb1, o1);
;                 const int w3 = wave & 3;
;                 const bf16x8 vs = w3 == 0 ? vB[0] : (w3 == 1 ? vB[1] : (w3 == 2 ? vB[2] : vB[3]));
;                 if (wave < 4) o0 = mfma32(atA, vs, o0); else o1 = mfma32(atA, vs, o1);
;                 unsigned* rb = red + (size_t)(rbuf * 8 + wave) * 1024 + lane; unsigned* rbx = red + (size_t)(rbuf * 8 + wave) * 1024 + (lane ^ 32);
; #pragma unroll
;                 for (int i = 0; i < 8; ++i) { unsigned* w_ = (i & 1) ? rbx : rb; w_[i * 64] = pk2(o0[2 * i], o0[2 * i + 1]); w_[512 + i * 64] = pk2(o1[2 * i], o1[2 * i + 1]); }
;             }
;             SCAN_GSTORE(nbuf, gcur);
;             __syncthreads();
;             if (gc < 512) {
	s_waitcnt vmcnt(12)
	ds_write_b128 v240, v[208:211]
	global_load_dwordx4 v[208:211], v[194:195], off
	v_lshl_add_u64 v[194:195], v[194:195], 0, v[254:255]
	v_cvt_pk_bf16_f32 v48, v0, v1
	v_cvt_pk_bf16_f32 v49, v2, v3
	v_cvt_pk_bf16_f32 v50, v4, v5
	v_cvt_pk_bf16_f32 v51, v6, v7
	v_cvt_pk_bf16_f32 v52, v8, v9
	v_cvt_pk_bf16_f32 v53, v10, v11
	v_cvt_pk_bf16_f32 v54, v12, v13
	v_cvt_pk_bf16_f32 v55, v14, v15
	v_mfma_f32_32x32x16_bf16 v[16:31], v[92:95], v[48:51], 0
	v_pk_mul_f32 v[0:1], v[178:179], v[0:1]
	v_pk_mul_f32 v[2:3], v[180:181], v[2:3]
	v_pk_mul_f32 v[4:5], v[182:183], v[4:5]
	v_mfma_f32_32x32x16_bf16 v[32:47], v[100:103], v[48:51], 0
	v_pk_mul_f32 v[6:7], v[184:185], v[6:7]
	v_pk_mul_f32 v[8:9], v[186:187], v[8:9]
	v_pk_mul_f32 v[10:11], v[188:189], v[10:11]
	v_mfma_f32_32x32x16_bf16 v[16:31], v[96:99], v[52:55], v[16:31]
	v_pk_mul_f32 v[12:13], v[190:191], v[12:13]
	v_pk_mul_f32 v[14:15], v[192:193], v[14:15]
	v_mfma_f32_32x32x16_bf16 v[32:47], v[104:107], v[52:55], v[32:47]
	v_mfma_f32_32x32x16_bf16 v[16:31], v[108:111], v[200:203], v[16:31]
	v_mfma_f32_32x32x16_bf16 v[0:15], v[112:115], v[144:147], v[0:15]
	v_mfma_f32_32x32x16_bf16 v[0:15], v[116:119], v[148:151], v[0:15]
	v_mfma_f32_32x32x16_bf16 v[0:15], v[120:123], v[152:155], v[0:15]
	v_mfma_f32_32x32x16_bf16 v[0:15], v[124:127], v[156:159], v[0:15]
	ds_read2st64_b64 v[212:215], v245 offset0:0 offset1:8
	ds_read2st64_b64 v[216:219], v245 offset0:16 offset1:24
	ds_read2st64_b64 v[220:223], v245 offset0:32 offset1:40
	ds_read2st64_b64 v[224:227], v245 offset0:48 offset1:56
	ds_read_b128 v[128:131], v246 offset:0
	global_load_dwordx4 v[112:115], v235, s[32:33]
	ds_read_b128 v[132:135], v246 offset:1024
	ds_read_b128 v[136:139], v246 offset:2048
	ds_read_b128 v[140:143], v246 offset:3072
	ds_read_b128 v[196:199], v248 offset:0
	ds_read_b128 v[162:165], v247 offset:0
	ds_read_b128 v[166:169], v247 offset:32
	ds_read_b128 v[170:173], v247 offset:64
	ds_read_b128 v[174:177], v247 offset:96
	s_waitcnt lgkmcnt(12)
	v_lshlrev_b32_e32 v229, 16, v213
	global_load_dwordx4 v[116:119], v235, s[32:33] offset:1024
	v_lshlrev_b32_e32 v228, 16, v212
	v_pk_add_f32 v[228:229], v[228:229], 0 op_sel_hi:[1,0]
	v_and_b32_e32 v231, 0xffff0000, v213
	v_and_b32_e32 v230, 0xffff0000, v212
	v_pk_add_f32 v[230:231], v[230:231], 0 op_sel_hi:[1,0]
	v_lshlrev_b32_e32 v49, 16, v215
	v_lshlrev_b32_e32 v48, 16, v214
	v_pk_add_f32 v[228:229], v[228:229], v[48:49]
	v_and_b32_e32 v215, 0xffff0000, v215
	v_and_b32_e32 v214, 0xffff0000, v214
	v_pk_add_f32 v[230:231], v[230:231], v[214:215]
	global_load_dwordx4 v[120:123], v235, s[32:33] offset:2048
	s_waitcnt lgkmcnt(11)
	v_lshlrev_b32_e32 v49, 16, v217
	v_lshlrev_b32_e32 v48, 16, v216
	v_pk_add_f32 v[228:229], v[228:229], v[48:49]
	v_and_b32_e32 v217, 0xffff0000, v217
	v_and_b32_e32 v216, 0xffff0000, v216
	v_pk_add_f32 v[230:231], v[230:231], v[216:217]
	v_lshlrev_b32_e32 v49, 16, v219
	v_lshlrev_b32_e32 v48, 16, v218
	v_pk_add_f32 v[228:229], v[228:229], v[48:49]
	global_load_dwordx4 v[124:127], v235, s[32:33] offset:3072
	v_and_b32_e32 v219, 0xffff0000, v219
	v_and_b32_e32 v218, 0xffff0000, v218
	v_pk_add_f32 v[230:231], v[230:231], v[218:219]
	s_waitcnt lgkmcnt(10)
	v_lshlrev_b32_e32 v49, 16, v221
	v_lshlrev_b32_e32 v48, 16, v220
	v_pk_add_f32 v[228:229], v[228:229], v[48:49]
	v_and_b32_e32 v221, 0xffff0000, v221
	v_and_b32_e32 v220, 0xffff0000, v220
	v_pk_add_f32 v[230:231], v[230:231], v[220:221]
	v_lshlrev_b32_e32 v49, 16, v223
	global_load_dwordx4 v[92:95], v232, s[34:35] offset:-4096
	v_lshlrev_b32_e32 v48, 16, v222
	v_pk_add_f32 v[228:229], v[228:229], v[48:49]
	v_and_b32_e32 v223, 0xffff0000, v223
	v_and_b32_e32 v222, 0xffff0000, v222
	v_pk_add_f32 v[230:231], v[230:231], v[222:223]
	s_waitcnt lgkmcnt(9)
	v_lshlrev_b32_e32 v49, 16, v225
	v_lshlrev_b32_e32 v48, 16, v224
	v_pk_add_f32 v[228:229], v[228:229], v[48:49]
	v_and_b32_e32 v225, 0xffff0000, v225
	v_and_b32_e32 v224, 0xffff0000, v224
	global_load_dwordx4 v[96:99], v232, s[34:35]
	v_pk_add_f32 v[230:231], v[230:231], v[224:225]
	v_lshlrev_b32_e32 v49, 16, v227
	v_lshlrev_b32_e32 v48, 16, v226
	v_pk_add_f32 v[228:229], v[228:229], v[48:49]
	v_and_b32_e32 v227, 0xffff0000, v227
	v_and_b32_e32 v226, 0xffff0000, v226
	v_pk_add_f32 v[230:231], v[230:231], v[226:227]
	v_cvt_pk_bf16_f32 v228, v228, v229
	v_cvt_pk_bf16_f32 v230, v230, v231
	global_store_dword v249, v228, s[38:39]
	global_load_dwordx4 v[100:103], v233, s[34:35] offset:-4096
	global_store_dword v250, v230, s[38:39]
	s_add_u32 s38, s38, s55
	s_addc_u32 s39, s39, s56
	v_cvt_pk_bf16_f32 v16, v16, v17
	v_cvt_pk_bf16_f32 v18, v18, v19
	v_cvt_pk_bf16_f32 v20, v20, v21
	v_cvt_pk_bf16_f32 v22, v22, v23
	v_cvt_pk_bf16_f32 v24, v24, v25
	v_cvt_pk_bf16_f32 v26, v26, v27
	v_cvt_pk_bf16_f32 v28, v28, v29
	v_cvt_pk_bf16_f32 v30, v30, v31
	global_load_dwordx4 v[104:107], v233, s[34:35]
	ds_write2st64_b32 v241, v16, v20 offset0:128 offset1:130
	ds_write2st64_b32 v242, v18, v22 offset0:129 offset1:131
	ds_write2st64_b32 v241, v24, v28 offset0:132 offset1:134
	ds_write2st64_b32 v242, v26, v30 offset0:133 offset1:135
	v_cvt_pk_bf16_f32 v32, v32, v33
	v_cvt_pk_bf16_f32 v34, v34, v35
	v_cvt_pk_bf16_f32 v36, v36, v37
	v_cvt_pk_bf16_f32 v38, v38, v39
	v_cvt_pk_bf16_f32 v40, v40, v41
	v_cvt_pk_bf16_f32 v42, v42, v43
	global_load_dwordx4 v[108:111], v251, s[36:37]
	v_cvt_pk_bf16_f32 v44, v44, v45
	v_cvt_pk_bf16_f32 v46, v46, v47
	ds_write2st64_b32 v243, v32, v36 offset0:128 offset1:130
	ds_write2st64_b32 v244, v34, v38 offset0:129 offset1:131
	ds_write2st64_b32 v243, v40, v44 offset0:132 offset1:134
	ds_write2st64_b32 v244, v42, v46 offset0:133 offset1:135
	s_add_u32 s32, s32, s53
	s_addc_u32 s33, s33, s56
	s_add_u32 s34, s34, s53
	s_addc_u32 s35, s35, s56
	s_add_u32 s36, s36, s54
	s_addc_u32 s37, s37, s56
	s_waitcnt lgkmcnt(0)
	s_barrier
	s_add_i32 s30, s30, 2
	s_cmp_lt_u32 s30, 256
	s_cbranch_scc1 .Lscan_loopA
	s_branch .Lscan_join
; __device__ __forceinline__ void phase_scan(const Args& a, unsigned char* smem, int tid, int lane, int wave) {
;     ...
;             const int rbuf = step & 1, nbuf = rbuf ^ 1;
;             if (gc < 512) {
;                 u32x4 s0, s1;
;                 s0.x = pk2(S[0], S[1]); s0.y = pk2(S[2], S[3]); s0.z = pk2(S[4], S[5]); s0.w = pk2(S[6], S[7]);
;                 s1.x = pk2(S[8], S[9]); s1.y = pk2(S[10], S[11]); s1.z = pk2(S[12], S[13]); s1.w = pk2(S[14], S[15]);
;                 const bf16x8 sb0 = __builtin_bit_cast(bf16x8, s0), sb1 = __builtin_bit_cast(bf16x8, s1);
;                 f32x16 o0, o1;
; #pragma unroll
;                 for (int i = 0; i < 16; ++i) { o0[i] = 0.f; o1[i] = 0.f; }
;                 o0 = mfma32(qeA[0], sb0, o0); o0 = mfma32(qeA[1], sb1, o0);
;                 o1 = mfma32(qeA[2], sb0, o1); o1 = mfma32(qeA[3], sb1, o1);
;                 const int w3 = wave & 3;
;                 const bf16x8 vs = w3 == 0 ? vB[0] : (w3 == 1 ? vB[1] : (w3 == 2 ? vB[2] : vB[3]));
;                 if (wave < 4) o0 = mfma32(atA, vs, o0); else o1 = mfma32(atA, vs, o1);
;                 unsigned* rb = red + (size_t)(rbuf * 8 + wave) * 1024 + lane; unsigned* rbx = red + (size_t)(rbuf * 8 + wave) * 1024 + (lane ^ 32);
; #pragma unroll
;                 for (int i = 0; i < 8; ++i) { unsigned* w_ = (i & 1) ? rbx : rb; w_[i * 64] = pk2(o0[2 * i], o0[2 * i + 1]); w_[512 + i * 64] = pk2(o1[2 * i], o1[2 * i + 1]); }
;             }
;             SCAN_GSTORE(nbuf, gcur);
;             __syncthreads();
;             if (gc < 512) {
;                 const int tp = tid >> 4, dv2 = (tid & 15) * 2, t = tp * 2, mt = t >> 5, tl = t & 31, pi = 2 * (tl >> 3) + ((tl & 3) >> 1), ln = ((tl >> 2) & 1) * 32 + dv2;
;                 const unsigned* rp = red + (size_t)rbuf * 8192 + (mt * 8 + pi) * 64 + (ln ^ ((pi & 1) << 5));
;                 float a0 = 0.f, a1 = 0.f, b0 = 0.f, b1 = 0.f;
; #pragma unroll
;                 for (int w = 0; w < 8; ++w) { const u32x2 v = *(const u32x2*)(rp + w * 1024); a0 += bflo(v.x); b0 += bfhi(v.x); a1 += bflo(v.y); b1 += bfhi(v.y); }
;                 bf16_t* op = O + (row0 + t) * 2048 + h * 512 + sl * 32 + dv2;
;                 *(unsigned*)op = pk2(a0, a1); *(unsigned*)(op + 2048) = pk2(b0, b1);
;             }
;             f32x4 ndl[4]; bf16x8 nvB[4];
;             SCAN_LREAD(nbuf, nvB, ndl);
; #pragma unroll
.Lscan_pathB:
	s_waitcnt vmcnt(10)
	ds_write_b128 v239, v[204:207]
	global_load_dwordx4 v[204:207], v[194:195], off
	v_lshl_add_u64 v[194:195], v[194:195], 0, v[254:255]
	v_cvt_pk_bf16_f32 v48, v0, v1
	v_cvt_pk_bf16_f32 v49, v2, v3
	v_cvt_pk_bf16_f32 v50, v4, v5
	v_cvt_pk_bf16_f32 v51, v6, v7
	v_cvt_pk_bf16_f32 v52, v8, v9
	v_cvt_pk_bf16_f32 v53, v10, v11
	v_cvt_pk_bf16_f32 v54, v12, v13
	v_cvt_pk_bf16_f32 v55, v14, v15
	v_mfma_f32_32x32x16_bf16 v[16:31], v[56:59], v[48:51], 0
	v_pk_mul_f32 v[0:1], v[162:163], v[0:1]
	v_pk_mul_f32 v[2:3], v[164:165], v[2:3]
	v_pk_mul_f32 v[4:5], v[166:167], v[4:5]
	v_mfma_f32_32x32x16_bf16 v[32:47], v[64:67], v[48:51], 0
	v_pk_mul_f32 v[6:7], v[168:169], v[6:7]
	v_pk_mul_f32 v[8:9], v[170:171], v[8:9]
	v_pk_mul_f32 v[10:11], v[172:173], v[10:11]
	v_mfma_f32_32x32x16_bf16 v[16:31], v[60:63], v[52:55], v[16:31]
	v_pk_mul_f32 v[12:13], v[174:175], v[12:13]
	v_pk_mul_f32 v[14:15], v[176:177], v[14:15]
	v_mfma_f32_32x32x16_bf16 v[32:47], v[68:71], v[52:55], v[32:47]
	v_mfma_f32_32x32x16_bf16 v[16:31], v[72:75], v[196:199], v[16:31]
	v_mfma_f32_32x32x16_bf16 v[0:15], v[76:79], v[128:131], v[0:15]
	v_mfma_f32_32x32x16_bf16 v[0:15], v[80:83], v[132:135], v[0:15]
	v_mfma_f32_32x32x16_bf16 v[0:15], v[84:87], v[136:139], v[0:15]
	v_mfma_f32_32x32x16_bf16 v[0:15], v[88:91], v[140:143], v[0:15]
	ds_read_b128 v[144:147], v246 offset:4096
	global_load_dwordx4 v[76:79], v235, s[32:33]
	ds_read_b128 v[148:151], v246 offset:5120
	ds_read_b128 v[152:155], v246 offset:6144
	ds_read_b128 v[156:159], v246 offset:7168
	ds_read_b128 v[200:203], v248 offset:4096
	global_load_dwordx4 v[80:83], v235, s[32:33] offset:1024
	ds_read_b128 v[178:181], v247 offset:1024
	ds_read_b128 v[182:185], v247 offset:1056
	ds_read_b128 v[186:189], v247 offset:1088
	ds_read_b128 v[190:193], v247 offset:1120
	global_load_dwordx4 v[84:87], v235, s[32:33] offset:2048
	v_cvt_pk_bf16_f32 v16, v16, v17
	v_cvt_pk_bf16_f32 v18, v18, v19
	v_cvt_pk_bf16_f32 v20, v20, v21
	global_load_dwordx4 v[88:91], v235, s[32:33] offset:3072
	v_cvt_pk_bf16_f32 v22, v22, v23
	v_cvt_pk_bf16_f32 v24, v24, v25
	v_cvt_pk_bf16_f32 v26, v26, v27
	v_cvt_pk_bf16_f32 v28, v28, v29
	global_load_dwordx4 v[56:59], v232, s[34:35] offset:-4096
	v_cvt_pk_bf16_f32 v30, v30, v31
	ds_write2st64_b32 v241, v16, v20 offset0:0 offset1:2
	ds_write2st64_b32 v242, v18, v22 offset0:1 offset1:3
	ds_write2st64_b32 v241, v24, v28 offset0:4 offset1:6
	global_load_dwordx4 v[60:63], v232, s[34:35]
	ds_write2st64_b32 v242, v26, v30 offset0:5 offset1:7
	v_cvt_pk_bf16_f32 v32, v32, v33
	v_cvt_pk_bf16_f32 v34, v34, v35
	global_load_dwordx4 v[64:67], v233, s[34:35] offset:-4096
	v_cvt_pk_bf16_f32 v36, v36, v37
	v_cvt_pk_bf16_f32 v38, v38, v39
	v_cvt_pk_bf16_f32 v40, v40, v41
	v_cvt_pk_bf16_f32 v42, v42, v43
	global_load_dwordx4 v[68:71], v233, s[34:35]
	v_cvt_pk_bf16_f32 v44, v44, v45
	v_cvt_pk_bf16_f32 v46, v46, v47
	ds_write2st64_b32 v243, v32, v36 offset0:0 offset1:2
	ds_write2st64_b32 v244, v34, v38 offset0:1 offset1:3
	global_load_dwordx4 v[72:75], v251, s[36:37]
	ds_write2st64_b32 v243, v40, v44 offset0:4 offset1:6
	ds_write2st64_b32 v244, v42, v46 offset0:5 offset1:7
	s_add_u32 s32, s32, s53
	s_addc_u32 s33, s33, s56
	s_add_u32 s34, s34, s53
	s_addc_u32 s35, s35, s56
	s_add_u32 s36, s36, s54
	s_addc_u32 s37, s37, s56
	s_waitcnt lgkmcnt(0)
	s_barrier
	s_waitcnt vmcnt(10)
	ds_write_b128 v240, v[208:211]
	global_load_dwordx4 v[208:211], v[194:195], off
	v_lshl_add_u64 v[194:195], v[194:195], 0, v[254:255]
	ds_read2st64_b64 v[212:215], v245 offset0:0 offset1:8
	ds_read2st64_b64 v[216:219], v245 offset0:16 offset1:24
	ds_read2st64_b64 v[220:223], v245 offset0:32 offset1:40
	ds_read2st64_b64 v[224:227], v245 offset0:48 offset1:56
	s_waitcnt lgkmcnt(3)
	v_lshlrev_b32_e32 v229, 16, v213
	v_lshlrev_b32_e32 v228, 16, v212
	v_pk_add_f32 v[228:229], v[228:229], 0 op_sel_hi:[1,0]
	v_and_b32_e32 v231, 0xffff0000, v213
	v_and_b32_e32 v230, 0xffff0000, v212
	v_pk_add_f32 v[230:231], v[230:231], 0 op_sel_hi:[1,0]
	v_lshlrev_b32_e32 v49, 16, v215
	v_lshlrev_b32_e32 v48, 16, v214
	v_pk_add_f32 v[228:229], v[228:229], v[48:49]
	v_and_b32_e32 v215, 0xffff0000, v215
	v_and_b32_e32 v214, 0xffff0000, v214
	v_pk_add_f32 v[230:231], v[230:231], v[214:215]
	s_waitcnt lgkmcnt(2)
	v_lshlrev_b32_e32 v49, 16, v217
	v_lshlrev_b32_e32 v48, 16, v216
	v_pk_add_f32 v[228:229], v[228:229], v[48:49]
	v_and_b32_e32 v217, 0xffff0000, v217
	v_and_b32_e32 v216, 0xffff0000, v216
	v_pk_add_f32 v[230:231], v[230:231], v[216:217]
	v_lshlrev_b32_e32 v49, 16, v219
	v_lshlrev_b32_e32 v48, 16, v218
	v_pk_add_f32 v[228:229], v[228:229], v[48:49]
	v_and_b32_e32 v219, 0xffff0000, v219
	v_and_b32_e32 v218, 0xffff0000, v218
	v_pk_add_f32 v[230:231], v[230:231], v[218:219]
	s_waitcnt lgkmcnt(1)
	v_lshlrev_b32_e32 v49, 16, v221
	v_lshlrev_b32_e32 v48, 16, v220
	v_pk_add_f32 v[228:229], v[228:229], v[48:49]
	v_and_b32_e32 v221, 0xffff0000, v221
	v_and_b32_e32 v220, 0xffff0000, v220
	v_pk_add_f32 v[230:231], v[230:231], v[220:221]
	v_lshlrev_b32_e32 v49, 16, v223
	v_lshlrev_b32_e32 v48, 16, v222
	v_pk_add_f32 v[228:229], v[228:229], v[48:49]
	v_and_b32_e32 v223, 0xffff0000, v223
	v_and_b32_e32 v222, 0xffff0000, v222
	v_pk_add_f32 v[230:231], v[230:231], v[222:223]
	s_waitcnt lgkmcnt(0)
; __device__ __forceinline__ void phase_scan(const Args& a, unsigned char* smem, int tid, int lane, int wave) {
;     ...
;             const int rbuf = step & 1, nbuf = rbuf ^ 1;
;             if (gc < 512) {
;                 u32x4 s0, s1;
;                 s0.x = pk2(S[0], S[1]); s0.y = pk2(S[2], S[3]); s0.z = pk2(S[4], S[5]); s0.w = pk2(S[6], S[7]);
;                 s1.x = pk2(S[8], S[9]); s1.y = pk2(S[10], S[11]); s1.z = pk2(S[12], S[13]); s1.w = pk2(S[14], S[15]);
;                 const bf16x8 sb0 = __builtin_bit_cast(bf16x8, s0), sb1 = __builtin_bit_cast(bf16x8, s1);
;                 f32x16 o0, o1;
; #pragma unroll
;                 for (int i = 0; i < 16; ++i) { o0[i] = 0.f; o1[i] = 0.f; }
;                 o0 = mfma32(qeA[0], sb0, o0); o0 = mfma32(qeA[1], sb1, o0);
;                 o1 = mfma32(qeA[2], sb0, o1); o1 = mfma32(qeA[3], sb1, o1);
;                 const int w3 = wave & 3;
;                 const bf16x8 vs = w3 == 0 ? vB[0] : (w3 == 1 ? vB[1] : (w3 == 2 ? vB[2] : vB[3]));
;                 if (wave < 4) o0 = mfma32(atA, vs, o0); else o1 = mfma32(atA, vs, o1);
;                 unsigned* rb = red + (size_t)(rbuf * 8 + wave) * 1024 + lane; unsigned* rbx = red + (size_t)(rbuf * 8 + wave) * 1024 + (lane ^ 32);
; #pragma unroll
;                 for (int i = 0; i < 8; ++i) { unsigned* w_ = (i & 1) ? rbx : rb; w_[i * 64] = pk2(o0[2 * i], o0[2 * i + 1]); w_[512 + i * 64] = pk2(o1[2 * i], o1[2 * i + 1]); }
;             }
;             SCAN_GSTORE(nbuf, gcur);
;             __syncthreads();
;             if (gc < 512) {
;                 const int tp = tid >> 4, dv2 = (tid & 15) * 2, t = tp * 2, mt = t >> 5, tl = t & 31, pi = 2 * (tl >> 3) + ((tl & 3) >> 1), ln = ((tl >> 2) & 1) * 32 + dv2;
;                 const unsigned* rp = red + (size_t)rbuf * 8192 + (mt * 8 + pi) * 64 + (ln ^ ((pi & 1) << 5));
;                 float a0 = 0.f, a1 = 0.f, b0 = 0.f, b1 = 0.f;
; #pragma unroll
;                 for (int w = 0; w < 8; ++w) { const u32x2 v = *(const u32x2*)(rp + w * 1024); a0 += bflo(v.x); b0 += bfhi(v.x); a1 += bflo(v.y); b1 += bfhi(v.y); }
;                 bf16_t* op = O + (row0 + t) * 2048 + h * 512 + sl * 32 + dv2;
;                 *(unsigned*)op = pk2(a0, a1); *(unsigned*)(op + 2048) = pk2(b0, b1);
;             }
;             f32x4 ndl[4]; bf16x8 nvB[4];
;             SCAN_LREAD(nbuf, nvB, ndl);
; #pragma unroll
	v_lshlrev_b32_e32 v49, 16, v225
	v_lshlrev_b32_e32 v48, 16, v224
	v_pk_add_f32 v[228:229], v[228:229], v[48:49]
	v_and_b32_e32 v225, 0xffff0000, v225
	v_and_b32_e32 v224, 0xffff0000, v224
	v_pk_add_f32 v[230:231], v[230:231], v[224:225]
	v_lshlrev_b32_e32 v49, 16, v227
	v_lshlrev_b32_e32 v48, 16, v226
	v_pk_add_f32 v[228:229], v[228:229], v[48:49]
	v_and_b32_e32 v227, 0xffff0000, v227
	v_and_b32_e32 v226, 0xffff0000, v226
	v_pk_add_f32 v[230:231], v[230:231], v[226:227]
	v_cvt_pk_bf16_f32 v228, v228, v229
	v_cvt_pk_bf16_f32 v230, v230, v231
	global_store_dword v249, v228, s[38:39]
	global_store_dword v250, v230, s[38:39]
	s_add_u32 s38, s38, s55
	s_addc_u32 s39, s39, s56
	v_cvt_pk_bf16_f32 v48, v0, v1
	v_cvt_pk_bf16_f32 v49, v2, v3
	v_cvt_pk_bf16_f32 v50, v4, v5
	v_cvt_pk_bf16_f32 v51, v6, v7
	v_cvt_pk_bf16_f32 v52, v8, v9
	v_cvt_pk_bf16_f32 v53, v10, v11
	v_cvt_pk_bf16_f32 v54, v12, v13
	v_cvt_pk_bf16_f32 v55, v14, v15
	v_mfma_f32_32x32x16_bf16 v[16:31], v[92:95], v[48:51], 0
	v_pk_mul_f32 v[0:1], v[178:179], v[0:1]
	v_pk_mul_f32 v[2:3], v[180:181], v[2:3]
	v_pk_mul_f32 v[4:5], v[182:183], v[4:5]
	v_mfma_f32_32x32x16_bf16 v[32:47], v[100:103], v[48:51], 0
	v_pk_mul_f32 v[6:7], v[184:185], v[6:7]
	v_pk_mul_f32 v[8:9], v[186:187], v[8:9]
	v_pk_mul_f32 v[10:11], v[188:189], v[10:11]
	v_mfma_f32_32x32x16_bf16 v[16:31], v[96:99], v[52:55], v[16:31]
	v_pk_mul_f32 v[12:13], v[190:191], v[12:13]
	v_pk_mul_f32 v[14:15], v[192:193], v[14:15]
	v_mfma_f32_32x32x16_bf16 v[32:47], v[104:107], v[52:55], v[32:47]
	v_mfma_f32_32x32x16_bf16 v[16:31], v[108:111], v[200:203], v[16:31]
	v_mfma_f32_32x32x16_bf16 v[0:15], v[112:115], v[144:147], v[0:15]
	v_mfma_f32_32x32x16_bf16 v[0:15], v[116:119], v[148:151], v[0:15]
	v_mfma_f32_32x32x16_bf16 v[0:15], v[120:123], v[152:155], v[0:15]
	v_mfma_f32_32x32x16_bf16 v[0:15], v[124:127], v[156:159], v[0:15]
	ds_read_b128 v[128:131], v246 offset:0
	global_load_dwordx4 v[112:115], v235, s[32:33]
	ds_read_b128 v[132:135], v246 offset:1024
	ds_read_b128 v[136:139], v246 offset:2048
	ds_read_b128 v[140:143], v246 offset:3072
	ds_read_b128 v[196:199], v248 offset:0
	global_load_dwordx4 v[116:119], v235, s[32:33] offset:1024
	ds_read_b128 v[162:165], v247 offset:0
	ds_read_b128 v[166:169], v247 offset:32
	ds_read_b128 v[170:173], v247 offset:64
	ds_read_b128 v[174:177], v247 offset:96
	global_load_dwordx4 v[120:123], v235, s[32:33] offset:2048
	v_cvt_pk_bf16_f32 v16, v16, v17
	v_cvt_pk_bf16_f32 v18, v18, v19
	v_cvt_pk_bf16_f32 v20, v20, v21
	global_load_dwordx4 v[124:127], v235, s[32:33] offset:3072
	v_cvt_pk_bf16_f32 v22, v22, v23
	v_cvt_pk_bf16_f32 v24, v24, v25
	v_cvt_pk_bf16_f32 v26, v26, v27
	v_cvt_pk_bf16_f32 v28, v28, v29
	global_load_dwordx4 v[92:95], v232, s[34:35] offset:-4096
	v_cvt_pk_bf16_f32 v30, v30, v31
	ds_write2st64_b32 v241, v16, v20 offset0:128 offset1:130
	ds_write2st64_b32 v242, v18, v22 offset0:129 offset1:131
	ds_write2st64_b32 v241, v24, v28 offset0:132 offset1:134
	global_load_dwordx4 v[96:99], v232, s[34:35]
	ds_write2st64_b32 v242, v26, v30 offset0:133 offset1:135
	v_cvt_pk_bf16_f32 v32, v32, v33
	v_cvt_pk_bf16_f32 v34, v34, v35
	global_load_dwordx4 v[100:103], v233, s[34:35] offset:-4096
	v_cvt_pk_bf16_f32 v36, v36, v37
	v_cvt_pk_bf16_f32 v38, v38, v39
	v_cvt_pk_bf16_f32 v40, v40, v41
	v_cvt_pk_bf16_f32 v42, v42, v43
	global_load_dwordx4 v[104:107], v233, s[34:35]
	v_cvt_pk_bf16_f32 v44, v44, v45
	v_cvt_pk_bf16_f32 v46, v46, v47
	ds_write2st64_b32 v243, v32, v36 offset0:128 offset1:130
	ds_write2st64_b32 v244, v34, v38 offset0:129 offset1:131
	global_load_dwordx4 v[108:111], v251, s[36:37]
	ds_write2st64_b32 v243, v40, v44 offset0:132 offset1:134
	ds_write2st64_b32 v244, v42, v46 offset0:133 offset1:135
	s_add_u32 s32, s32, s53
	s_addc_u32 s33, s33, s56
	s_add_u32 s34, s34, s53
	s_addc_u32 s35, s35, s56
	s_add_u32 s36, s36, s54
	s_addc_u32 s37, s37, s56
	s_waitcnt lgkmcnt(0)
	s_barrier
	s_waitcnt vmcnt(12)
	ds_write_b128 v239, v[204:207]
	global_load_dwordx4 v[204:207], v[194:195], off
	v_lshl_add_u64 v[194:195], v[194:195], 0, v[254:255]
	ds_read2st64_b64 v[212:215], v245 offset0:64 offset1:72
	ds_read2st64_b64 v[216:219], v245 offset0:80 offset1:88
	ds_read2st64_b64 v[220:223], v245 offset0:96 offset1:104
	ds_read2st64_b64 v[224:227], v245 offset0:112 offset1:120
	s_waitcnt lgkmcnt(3)
	v_lshlrev_b32_e32 v229, 16, v213
	v_lshlrev_b32_e32 v228, 16, v212
	v_pk_add_f32 v[228:229], v[228:229], 0 op_sel_hi:[1,0]
	v_and_b32_e32 v231, 0xffff0000, v213
	v_and_b32_e32 v230, 0xffff0000, v212
	v_pk_add_f32 v[230:231], v[230:231], 0 op_sel_hi:[1,0]
	v_lshlrev_b32_e32 v49, 16, v215
	v_lshlrev_b32_e32 v48, 16, v214
	v_pk_add_f32 v[228:229], v[228:229], v[48:49]
	v_and_b32_e32 v215, 0xffff0000, v215
	v_and_b32_e32 v214, 0xffff0000, v214
	v_pk_add_f32 v[230:231], v[230:231], v[214:215]
	s_waitcnt lgkmcnt(2)
	v_lshlrev_b32_e32 v49, 16, v217
	v_lshlrev_b32_e32 v48, 16, v216
	v_pk_add_f32 v[228:229], v[228:229], v[48:49]
	v_and_b32_e32 v217, 0xffff0000, v217
	v_and_b32_e32 v216, 0xffff0000, v216
	v_pk_add_f32 v[230:231], v[230:231], v[216:217]
	v_lshlrev_b32_e32 v49, 16, v219
	v_lshlrev_b32_e32 v48, 16, v218
	v_pk_add_f32 v[228:229], v[228:229], v[48:49]
	v_and_b32_e32 v219, 0xffff0000, v219
	v_and_b32_e32 v218, 0xffff0000, v218
	v_pk_add_f32 v[230:231], v[230:231], v[218:219]
	s_waitcnt lgkmcnt(1)
	v_lshlrev_b32_e32 v49, 16, v221
	v_lshlrev_b32_e32 v48, 16, v220
	v_pk_add_f32 v[228:229], v[228:229], v[48:49]
	v_and_b32_e32 v221, 0xffff0000, v221
	v_and_b32_e32 v220, 0xffff0000, v220
	v_pk_add_f32 v[230:231], v[230:231], v[220:221]
	v_lshlrev_b32_e32 v49, 16, v223
	v_lshlrev_b32_e32 v48, 16, v222
	v_pk_add_f32 v[228:229], v[228:229], v[48:49]
	v_and_b32_e32 v223, 0xffff0000, v223
	v_and_b32_e32 v222, 0xffff0000, v222
	v_pk_add_f32 v[230:231], v[230:231], v[222:223]
	s_waitcnt lgkmcnt(0)
; __device__ __forceinline__ void phase_scan(const Args& a, unsigned char* smem, int tid, int lane, int wave) {
;     ...
;             const int rbuf = step & 1, nbuf = rbuf ^ 1;
;             if (gc < 512) {
;                 u32x4 s0, s1;
;                 s0.x = pk2(S[0], S[1]); s0.y = pk2(S[2], S[3]); s0.z = pk2(S[4], S[5]); s0.w = pk2(S[6], S[7]);
;                 s1.x = pk2(S[8], S[9]); s1.y = pk2(S[10], S[11]); s1.z = pk2(S[12], S[13]); s1.w = pk2(S[14], S[15]);
;                 const bf16x8 sb0 = __builtin_bit_cast(bf16x8, s0), sb1 = __builtin_bit_cast(bf16x8, s1);
;                 f32x16 o0, o1;
; #pragma unroll
;                 for (int i = 0; i < 16; ++i) { o0[i] = 0.f; o1[i] = 0.f; }
;                 o0 = mfma32(qeA[0], sb0, o0); o0 = mfma32(qeA[1], sb1, o0);
;                 o1 = mfma32(qeA[2], sb0, o1); o1 = mfma32(qeA[3], sb1, o1);
;                 const int w3 = wave & 3;
;                 const bf16x8 vs = w3 == 0 ? vB[0] : (w3 == 1 ? vB[1] : (w3 == 2 ? vB[2] : vB[3]));
;                 if (wave < 4) o0 = mfma32(atA, vs, o0); else o1 = mfma32(atA, vs, o1);
;                 unsigned* rb = red + (size_t)(rbuf * 8 + wave) * 1024 + lane; unsigned* rbx = red + (size_t)(rbuf * 8 + wave) * 1024 + (lane ^ 32);
; #pragma unroll
;                 for (int i = 0; i < 8; ++i) { unsigned* w_ = (i & 1) ? rbx : rb; w_[i * 64] = pk2(o0[2 * i], o0[2 * i + 1]); w_[512 + i * 64] = pk2(o1[2 * i], o1[2 * i + 1]); }
;             }
;             SCAN_GSTORE(nbuf, gcur);
;             __syncthreads();
;             if (gc < 512) {
;                 const int tp = tid >> 4, dv2 = (tid & 15) * 2, t = tp * 2, mt = t >> 5, tl = t & 31, pi = 2 * (tl >> 3) + ((tl & 3) >> 1), ln = ((tl >> 2) & 1) * 32 + dv2;
;                 const unsigned* rp = red + (size_t)rbuf * 8192 + (mt * 8 + pi) * 64 + (ln ^ ((pi & 1) << 5));
;                 float a0 = 0.f, a1 = 0.f, b0 = 0.f, b1 = 0.f;
; #pragma unroll
;                 for (int w = 0; w < 8; ++w) { const u32x2 v = *(const u32x2*)(rp + w * 1024); a0 += bflo(v.x); b0 += bfhi(v.x); a1 += bflo(v.y); b1 += bfhi(v.y); }
;                 bf16_t* op = O + (row0 + t) * 2048 + h * 512 + sl * 32 + dv2;
;                 *(unsigned*)op = pk2(a0, a1); *(unsigned*)(op + 2048) = pk2(b0, b1);
;             }
;             f32x4 ndl[4]; bf16x8 nvB[4];
;             SCAN_LREAD(nbuf, nvB, ndl);
; #pragma unroll
	v_lshlrev_b32_e32 v49, 16, v225
	v_lshlrev_b32_e32 v48, 16, v224
	v_pk_add_f32 v[228:229], v[228:229], v[48:49]
	v_and_b32_e32 v225, 0xffff0000, v225
	v_and_b32_e32 v224, 0xffff0000, v224
	v_pk_add_f32 v[230:231], v[230:231], v[224:225]
	v_lshlrev_b32_e32 v49, 16, v227
	v_lshlrev_b32_e32 v48, 16, v226
	v_pk_add_f32 v[228:229], v[228:229], v[48:49]
	v_and_b32_e32 v227, 0xffff0000, v227
	v_and_b32_e32 v226, 0xffff0000, v226
	v_pk_add_f32 v[230:231], v[230:231], v[226:227]
	v_cvt_pk_bf16_f32 v228, v228, v229
	v_cvt_pk_bf16_f32 v230, v230, v231
	global_store_dword v249, v228, s[38:39]
	global_store_dword v250, v230, s[38:39]
	s_add_u32 s38, s38, s55
	s_addc_u32 s39, s39, s56
	v_cvt_pk_bf16_f32 v48, v0, v1
	v_cvt_pk_bf16_f32 v49, v2, v3
	v_cvt_pk_bf16_f32 v50, v4, v5
	v_cvt_pk_bf16_f32 v51, v6, v7
	v_cvt_pk_bf16_f32 v52, v8, v9
	v_cvt_pk_bf16_f32 v53, v10, v11
	v_cvt_pk_bf16_f32 v54, v12, v13
	v_cvt_pk_bf16_f32 v55, v14, v15
	v_mfma_f32_32x32x16_bf16 v[16:31], v[56:59], v[48:51], 0
	v_pk_mul_f32 v[0:1], v[162:163], v[0:1]
	v_pk_mul_f32 v[2:3], v[164:165], v[2:3]
	v_pk_mul_f32 v[4:5], v[166:167], v[4:5]
	v_mfma_f32_32x32x16_bf16 v[32:47], v[64:67], v[48:51], 0
	v_pk_mul_f32 v[6:7], v[168:169], v[6:7]
	v_pk_mul_f32 v[8:9], v[170:171], v[8:9]
	v_pk_mul_f32 v[10:11], v[172:173], v[10:11]
	v_mfma_f32_32x32x16_bf16 v[16:31], v[60:63], v[52:55], v[16:31]
	v_pk_mul_f32 v[12:13], v[174:175], v[12:13]
	v_pk_mul_f32 v[14:15], v[176:177], v[14:15]
	v_mfma_f32_32x32x16_bf16 v[32:47], v[68:71], v[52:55], v[32:47]
	v_mfma_f32_32x32x16_bf16 v[16:31], v[72:75], v[196:199], v[16:31]
	v_mfma_f32_32x32x16_bf16 v[0:15], v[76:79], v[128:131], v[0:15]
	v_mfma_f32_32x32x16_bf16 v[0:15], v[80:83], v[132:135], v[0:15]
	v_mfma_f32_32x32x16_bf16 v[0:15], v[84:87], v[136:139], v[0:15]
	v_mfma_f32_32x32x16_bf16 v[0:15], v[88:91], v[140:143], v[0:15]
	ds_read_b128 v[144:147], v246 offset:4096
	global_load_dwordx4 v[76:79], v235, s[32:33]
	ds_read_b128 v[148:151], v246 offset:5120
	ds_read_b128 v[152:155], v246 offset:6144
	ds_read_b128 v[156:159], v246 offset:7168
	ds_read_b128 v[200:203], v248 offset:4096
	global_load_dwordx4 v[80:83], v235, s[32:33] offset:1024
	ds_read_b128 v[178:181], v247 offset:1024
	ds_read_b128 v[182:185], v247 offset:1056
	ds_read_b128 v[186:189], v247 offset:1088
	ds_read_b128 v[190:193], v247 offset:1120
	global_load_dwordx4 v[84:87], v235, s[32:33] offset:2048
	v_cvt_pk_bf16_f32 v16, v16, v17
	v_cvt_pk_bf16_f32 v18, v18, v19
	v_cvt_pk_bf16_f32 v20, v20, v21
	global_load_dwordx4 v[88:91], v235, s[32:33] offset:3072
	v_cvt_pk_bf16_f32 v22, v22, v23
	v_cvt_pk_bf16_f32 v24, v24, v25
	v_cvt_pk_bf16_f32 v26, v26, v27
	v_cvt_pk_bf16_f32 v28, v28, v29
	global_load_dwordx4 v[56:59], v232, s[34:35] offset:-4096
	v_cvt_pk_bf16_f32 v30, v30, v31
	ds_write2st64_b32 v241, v16, v20 offset0:0 offset1:2
	ds_write2st64_b32 v242, v18, v22 offset0:1 offset1:3
	ds_write2st64_b32 v241, v24, v28 offset0:4 offset1:6
	global_load_dwordx4 v[60:63], v232, s[34:35]
	ds_write2st64_b32 v242, v26, v30 offset0:5 offset1:7
	v_cvt_pk_bf16_f32 v32, v32, v33
	v_cvt_pk_bf16_f32 v34, v34, v35
	global_load_dwordx4 v[64:67], v233, s[34:35] offset:-4096
	v_cvt_pk_bf16_f32 v36, v36, v37
	v_cvt_pk_bf16_f32 v38, v38, v39
	v_cvt_pk_bf16_f32 v40, v40, v41
	v_cvt_pk_bf16_f32 v42, v42, v43
	global_load_dwordx4 v[68:71], v233, s[34:35]
	v_cvt_pk_bf16_f32 v44, v44, v45
	v_cvt_pk_bf16_f32 v46, v46, v47
	ds_write2st64_b32 v243, v32, v36 offset0:0 offset1:2
	ds_write2st64_b32 v244, v34, v38 offset0:1 offset1:3
	global_load_dwordx4 v[72:75], v251, s[36:37]
	ds_write2st64_b32 v243, v40, v44 offset0:4 offset1:6
	ds_write2st64_b32 v244, v42, v46 offset0:5 offset1:7
	s_add_u32 s32, s32, s53
	s_addc_u32 s33, s33, s56
	s_add_u32 s34, s34, s53
	s_addc_u32 s35, s35, s56
	s_add_u32 s36, s36, s54
	s_addc_u32 s37, s37, s56
	s_waitcnt lgkmcnt(0)
	s_barrier
	s_waitcnt vmcnt(12)
	ds_write_b128 v240, v[208:211]
	global_load_dwordx4 v[208:211], v[194:195], off
	v_lshl_add_u64 v[194:195], v[194:195], 0, v[254:255]
	ds_read2st64_b64 v[212:215], v245 offset0:0 offset1:8
	ds_read2st64_b64 v[216:219], v245 offset0:16 offset1:24
	ds_read2st64_b64 v[220:223], v245 offset0:32 offset1:40
	ds_read2st64_b64 v[224:227], v245 offset0:48 offset1:56
	s_waitcnt lgkmcnt(3)
	v_lshlrev_b32_e32 v229, 16, v213
	v_lshlrev_b32_e32 v228, 16, v212
	v_pk_add_f32 v[228:229], v[228:229], 0 op_sel_hi:[1,0]
	v_and_b32_e32 v231, 0xffff0000, v213
	v_and_b32_e32 v230, 0xffff0000, v212
	v_pk_add_f32 v[230:231], v[230:231], 0 op_sel_hi:[1,0]
	v_lshlrev_b32_e32 v49, 16, v215
	v_lshlrev_b32_e32 v48, 16, v214
	v_pk_add_f32 v[228:229], v[228:229], v[48:49]
	v_and_b32_e32 v215, 0xffff0000, v215
	v_and_b32_e32 v214, 0xffff0000, v214
	v_pk_add_f32 v[230:231], v[230:231], v[214:215]
	s_waitcnt lgkmcnt(2)
	v_lshlrev_b32_e32 v49, 16, v217
	v_lshlrev_b32_e32 v48, 16, v216
	v_pk_add_f32 v[228:229], v[228:229], v[48:49]
	v_and_b32_e32 v217, 0xffff0000, v217
	v_and_b32_e32 v216, 0xffff0000, v216
	v_pk_add_f32 v[230:231], v[230:231], v[216:217]
	v_lshlrev_b32_e32 v49, 16, v219
	v_lshlrev_b32_e32 v48, 16, v218
	v_pk_add_f32 v[228:229], v[228:229], v[48:49]
	v_and_b32_e32 v219, 0xffff0000, v219
	v_and_b32_e32 v218, 0xffff0000, v218
	v_pk_add_f32 v[230:231], v[230:231], v[218:219]
	s_waitcnt lgkmcnt(1)
	v_lshlrev_b32_e32 v49, 16, v221
	v_lshlrev_b32_e32 v48, 16, v220
	v_pk_add_f32 v[228:229], v[228:229], v[48:49]
	v_and_b32_e32 v221, 0xffff0000, v221
	v_and_b32_e32 v220, 0xffff0000, v220
	v_pk_add_f32 v[230:231], v[230:231], v[220:221]
	v_lshlrev_b32_e32 v49, 16, v223
	v_lshlrev_b32_e32 v48, 16, v222
	v_pk_add_f32 v[228:229], v[228:229], v[48:49]
	v_and_b32_e32 v223, 0xffff0000, v223
	v_and_b32_e32 v222, 0xffff0000, v222
	v_pk_add_f32 v[230:231], v[230:231], v[222:223]
	s_waitcnt lgkmcnt(0)
; __device__ __forceinline__ void phase_scan(const Args& a, unsigned char* smem, int tid, int lane, int wave) {
;     ...
;             const int rbuf = step & 1, nbuf = rbuf ^ 1;
;             if (gc < 512) {
;                 u32x4 s0, s1;
;                 s0.x = pk2(S[0], S[1]); s0.y = pk2(S[2], S[3]); s0.z = pk2(S[4], S[5]); s0.w = pk2(S[6], S[7]);
;                 s1.x = pk2(S[8], S[9]); s1.y = pk2(S[10], S[11]); s1.z = pk2(S[12], S[13]); s1.w = pk2(S[14], S[15]);
;                 const bf16x8 sb0 = __builtin_bit_cast(bf16x8, s0), sb1 = __builtin_bit_cast(bf16x8, s1);
;                 f32x16 o0, o1;
; #pragma unroll
;                 for (int i = 0; i < 16; ++i) { o0[i] = 0.f; o1[i] = 0.f; }
;                 o0 = mfma32(qeA[0], sb0, o0); o0 = mfma32(qeA[1], sb1, o0);
;                 o1 = mfma32(qeA[2], sb0, o1); o1 = mfma32(qeA[3], sb1, o1);
;                 const int w3 = wave & 3;
;                 const bf16x8 vs = w3 == 0 ? vB[0] : (w3 == 1 ? vB[1] : (w3 == 2 ? vB[2] : vB[3]));
;                 if (wave < 4) o0 = mfma32(atA, vs, o0); else o1 = mfma32(atA, vs, o1);
;                 unsigned* rb = red + (size_t)(rbuf * 8 + wave) * 1024 + lane; unsigned* rbx = red + (size_t)(rbuf * 8 + wave) * 1024 + (lane ^ 32);
; #pragma unroll
;                 for (int i = 0; i < 8; ++i) { unsigned* w_ = (i & 1) ? rbx : rb; w_[i * 64] = pk2(o0[2 * i], o0[2 * i + 1]); w_[512 + i * 64] = pk2(o1[2 * i], o1[2 * i + 1]); }
;             }
;             SCAN_GSTORE(nbuf, gcur);
;             __syncthreads();
;             if (gc < 512) {
;                 const int tp = tid >> 4, dv2 = (tid & 15) * 2, t = tp * 2, mt = t >> 5, tl = t & 31, pi = 2 * (tl >> 3) + ((tl & 3) >> 1), ln = ((tl >> 2) & 1) * 32 + dv2;
;                 const unsigned* rp = red + (size_t)rbuf * 8192 + (mt * 8 + pi) * 64 + (ln ^ ((pi & 1) << 5));
;                 float a0 = 0.f, a1 = 0.f, b0 = 0.f, b1 = 0.f;
; #pragma unroll
;                 for (int w = 0; w < 8; ++w) { const u32x2 v = *(const u32x2*)(rp + w * 1024); a0 += bflo(v.x); b0 += bfhi(v.x); a1 += bflo(v.y); b1 += bfhi(v.y); }
;                 bf16_t* op = O + (row0 + t) * 2048 + h * 512 + sl * 32 + dv2;
;                 *(unsigned*)op = pk2(a0, a1); *(unsigned*)(op + 2048) = pk2(b0, b1);
;             }
;             f32x4 ndl[4]; bf16x8 nvB[4];
;             SCAN_LREAD(nbuf, nvB, ndl);
; #pragma unroll
	v_lshlrev_b32_e32 v49, 16, v225
	v_lshlrev_b32_e32 v48, 16, v224
	v_pk_add_f32 v[228:229], v[228:229], v[48:49]
	v_and_b32_e32 v225, 0xffff0000, v225
	v_and_b32_e32 v224, 0xffff0000, v224
	v_pk_add_f32 v[230:231], v[230:231], v[224:225]
	v_lshlrev_b32_e32 v49, 16, v227
	v_lshlrev_b32_e32 v48, 16, v226
	v_pk_add_f32 v[228:229], v[228:229], v[48:49]
	v_and_b32_e32 v227, 0xffff0000, v227
	v_and_b32_e32 v226, 0xffff0000, v226
	v_pk_add_f32 v[230:231], v[230:231], v[226:227]
	v_cvt_pk_bf16_f32 v228, v228, v229
	v_cvt_pk_bf16_f32 v230, v230, v231
	global_store_dword v249, v228, s[38:39]
	global_store_dword v250, v230, s[38:39]
	s_add_u32 s38, s38, s55
	s_addc_u32 s39, s39, s56
	v_cvt_pk_bf16_f32 v48, v0, v1
	v_cvt_pk_bf16_f32 v49, v2, v3
	v_cvt_pk_bf16_f32 v50, v4, v5
	v_cvt_pk_bf16_f32 v51, v6, v7
	v_cvt_pk_bf16_f32 v52, v8, v9
	v_cvt_pk_bf16_f32 v53, v10, v11
	v_cvt_pk_bf16_f32 v54, v12, v13
	v_cvt_pk_bf16_f32 v55, v14, v15
	v_mfma_f32_32x32x16_bf16 v[16:31], v[92:95], v[48:51], 0
	v_pk_mul_f32 v[0:1], v[178:179], v[0:1]
	v_pk_mul_f32 v[2:3], v[180:181], v[2:3]
	v_pk_mul_f32 v[4:5], v[182:183], v[4:5]
	v_mfma_f32_32x32x16_bf16 v[32:47], v[100:103], v[48:51], 0
	v_pk_mul_f32 v[6:7], v[184:185], v[6:7]
	v_pk_mul_f32 v[8:9], v[186:187], v[8:9]
	v_pk_mul_f32 v[10:11], v[188:189], v[10:11]
	v_mfma_f32_32x32x16_bf16 v[16:31], v[96:99], v[52:55], v[16:31]
	v_pk_mul_f32 v[12:13], v[190:191], v[12:13]
	v_pk_mul_f32 v[14:15], v[192:193], v[14:15]
	v_mfma_f32_32x32x16_bf16 v[32:47], v[104:107], v[52:55], v[32:47]
	v_mfma_f32_32x32x16_bf16 v[16:31], v[108:111], v[200:203], v[16:31]
	v_mfma_f32_32x32x16_bf16 v[0:15], v[112:115], v[144:147], v[0:15]
	v_mfma_f32_32x32x16_bf16 v[0:15], v[116:119], v[148:151], v[0:15]
	v_mfma_f32_32x32x16_bf16 v[0:15], v[120:123], v[152:155], v[0:15]
	v_mfma_f32_32x32x16_bf16 v[0:15], v[124:127], v[156:159], v[0:15]
	ds_read_b128 v[128:131], v246 offset:0
	global_load_dwordx4 v[112:115], v235, s[32:33]
	ds_read_b128 v[132:135], v246 offset:1024
	ds_read_b128 v[136:139], v246 offset:2048
	ds_read_b128 v[140:143], v246 offset:3072
	ds_read_b128 v[196:199], v248 offset:0
	global_load_dwordx4 v[116:119], v235, s[32:33] offset:1024
	ds_read_b128 v[162:165], v247 offset:0
	ds_read_b128 v[166:169], v247 offset:32
	ds_read_b128 v[170:173], v247 offset:64
	ds_read_b128 v[174:177], v247 offset:96
	global_load_dwordx4 v[120:123], v235, s[32:33] offset:2048
	v_cvt_pk_bf16_f32 v16, v16, v17
	v_cvt_pk_bf16_f32 v18, v18, v19
	v_cvt_pk_bf16_f32 v20, v20, v21
	global_load_dwordx4 v[124:127], v235, s[32:33] offset:3072
	v_cvt_pk_bf16_f32 v22, v22, v23
	v_cvt_pk_bf16_f32 v24, v24, v25
	v_cvt_pk_bf16_f32 v26, v26, v27
	v_cvt_pk_bf16_f32 v28, v28, v29
	global_load_dwordx4 v[92:95], v232, s[34:35] offset:-4096
	v_cvt_pk_bf16_f32 v30, v30, v31
	ds_write2st64_b32 v241, v16, v20 offset0:128 offset1:130
	ds_write2st64_b32 v242, v18, v22 offset0:129 offset1:131
	ds_write2st64_b32 v241, v24, v28 offset0:132 offset1:134
	global_load_dwordx4 v[96:99], v232, s[34:35]
	ds_write2st64_b32 v242, v26, v30 offset0:133 offset1:135
	v_cvt_pk_bf16_f32 v32, v32, v33
	v_cvt_pk_bf16_f32 v34, v34, v35
	global_load_dwordx4 v[100:103], v233, s[34:35] offset:-4096
	v_cvt_pk_bf16_f32 v36, v36, v37
	v_cvt_pk_bf16_f32 v38, v38, v39
	v_cvt_pk_bf16_f32 v40, v40, v41
	v_cvt_pk_bf16_f32 v42, v42, v43
	global_load_dwordx4 v[104:107], v233, s[34:35]
	v_cvt_pk_bf16_f32 v44, v44, v45
	v_cvt_pk_bf16_f32 v46, v46, v47
	ds_write2st64_b32 v243, v32, v36 offset0:128 offset1:130
	ds_write2st64_b32 v244, v34, v38 offset0:129 offset1:131
	global_load_dwordx4 v[108:111], v251, s[36:37]
	ds_write2st64_b32 v243, v40, v44 offset0:132 offset1:134
	ds_write2st64_b32 v244, v42, v46 offset0:133 offset1:135
	s_add_u32 s32, s32, s53
	s_addc_u32 s33, s33, s56
	s_add_u32 s34, s34, s53
	s_addc_u32 s35, s35, s56
	s_add_u32 s36, s36, s54
	s_addc_u32 s37, s37, s56
	s_waitcnt lgkmcnt(0)
	s_barrier
	s_mov_b32 s30, 4
.Lscan_loopB:
	s_waitcnt vmcnt(12)
	ds_write_b128 v239, v[204:207]
	global_load_dwordx4 v[204:207], v[194:195], off
	v_lshl_add_u64 v[194:195], v[194:195], 0, v[254:255]
	ds_read2st64_b64 v[212:215], v245 offset0:64 offset1:72
	ds_read2st64_b64 v[216:219], v245 offset0:80 offset1:88
	ds_read2st64_b64 v[220:223], v245 offset0:96 offset1:104
	ds_read2st64_b64 v[224:227], v245 offset0:112 offset1:120
	s_waitcnt lgkmcnt(3)
	v_lshlrev_b32_e32 v229, 16, v213
	v_lshlrev_b32_e32 v228, 16, v212
	v_pk_add_f32 v[228:229], v[228:229], 0 op_sel_hi:[1,0]
	v_and_b32_e32 v231, 0xffff0000, v213
	v_and_b32_e32 v230, 0xffff0000, v212
	v_pk_add_f32 v[230:231], v[230:231], 0 op_sel_hi:[1,0]
	v_lshlrev_b32_e32 v49, 16, v215
	v_lshlrev_b32_e32 v48, 16, v214
	v_pk_add_f32 v[228:229], v[228:229], v[48:49]
	v_and_b32_e32 v215, 0xffff0000, v215
	v_and_b32_e32 v214, 0xffff0000, v214
	v_pk_add_f32 v[230:231], v[230:231], v[214:215]
	s_waitcnt lgkmcnt(2)
	v_lshlrev_b32_e32 v49, 16, v217
	v_lshlrev_b32_e32 v48, 16, v216
	v_pk_add_f32 v[228:229], v[228:229], v[48:49]
	v_and_b32_e32 v217, 0xffff0000, v217
	v_and_b32_e32 v216, 0xffff0000, v216
	v_pk_add_f32 v[230:231], v[230:231], v[216:217]
	v_lshlrev_b32_e32 v49, 16, v219
	v_lshlrev_b32_e32 v48, 16, v218
	v_pk_add_f32 v[228:229], v[228:229], v[48:49]
	v_and_b32_e32 v219, 0xffff0000, v219
	v_and_b32_e32 v218, 0xffff0000, v218
	v_pk_add_f32 v[230:231], v[230:231], v[218:219]
	s_waitcnt lgkmcnt(1)
	v_lshlrev_b32_e32 v49, 16, v221
	v_lshlrev_b32_e32 v48, 16, v220
	v_pk_add_f32 v[228:229], v[228:229], v[48:49]
	v_and_b32_e32 v221, 0xffff0000, v221
	v_and_b32_e32 v220, 0xffff0000, v220
	v_pk_add_f32 v[230:231], v[230:231], v[220:221]
	v_lshlrev_b32_e32 v49, 16, v223
	v_lshlrev_b32_e32 v48, 16, v222
	v_pk_add_f32 v[228:229], v[228:229], v[48:49]
	v_and_b32_e32 v223, 0xffff0000, v223
	v_and_b32_e32 v222, 0xffff0000, v222
	v_pk_add_f32 v[230:231], v[230:231], v[222:223]
	s_waitcnt lgkmcnt(0)
; __device__ __forceinline__ void phase_scan(const Args& a, unsigned char* smem, int tid, int lane, int wave) {
;     ...
;             const int rbuf = step & 1, nbuf = rbuf ^ 1;
;             if (gc < 512) {
;                 u32x4 s0, s1;
;                 s0.x = pk2(S[0], S[1]); s0.y = pk2(S[2], S[3]); s0.z = pk2(S[4], S[5]); s0.w = pk2(S[6], S[7]);
;                 s1.x = pk2(S[8], S[9]); s1.y = pk2(S[10], S[11]); s1.z = pk2(S[12], S[13]); s1.w = pk2(S[14], S[15]);
;                 const bf16x8 sb0 = __builtin_bit_cast(bf16x8, s0), sb1 = __builtin_bit_cast(bf16x8, s1);
;                 f32x16 o0, o1;
; #pragma unroll
;                 for (int i = 0; i < 16; ++i) { o0[i] = 0.f; o1[i] = 0.f; }
;                 o0 = mfma32(qeA[0], sb0, o0); o0 = mfma32(qeA[1], sb1, o0);
;                 o1 = mfma32(qeA[2], sb0, o1); o1 = mfma32(qeA[3], sb1, o1);
;                 const int w3 = wave & 3;
;                 const bf16x8 vs = w3 == 0 ? vB[0] : (w3 == 1 ? vB[1] : (w3 == 2 ? vB[2] : vB[3]));
;                 if (wave < 4) o0 = mfma32(atA, vs, o0); else o1 = mfma32(atA, vs, o1);
;                 unsigned* rb = red + (size_t)(rbuf * 8 + wave) * 1024 + lane; unsigned* rbx = red + (size_t)(rbuf * 8 + wave) * 1024 + (lane ^ 32);
; #pragma unroll
;                 for (int i = 0; i < 8; ++i) { unsigned* w_ = (i & 1) ? rbx : rb; w_[i * 64] = pk2(o0[2 * i], o0[2 * i + 1]); w_[512 + i * 64] = pk2(o1[2 * i], o1[2 * i + 1]); }
;             }
;             SCAN_GSTORE(nbuf, gcur);
;             __syncthreads();
;             if (gc < 512) {
;                 const int tp = tid >> 4, dv2 = (tid & 15) * 2, t = tp * 2, mt = t >> 5, tl = t & 31, pi = 2 * (tl >> 3) + ((tl & 3) >> 1), ln = ((tl >> 2) & 1) * 32 + dv2;
;                 const unsigned* rp = red + (size_t)rbuf * 8192 + (mt * 8 + pi) * 64 + (ln ^ ((pi & 1) << 5));
;                 float a0 = 0.f, a1 = 0.f, b0 = 0.f, b1 = 0.f;
; #pragma unroll
;                 for (int w = 0; w < 8; ++w) { const u32x2 v = *(const u32x2*)(rp + w * 1024); a0 += bflo(v.x); b0 += bfhi(v.x); a1 += bflo(v.y); b1 += bfhi(v.y); }
;                 bf16_t* op = O + (row0 + t) * 2048 + h * 512 + sl * 32 + dv2;
;                 *(unsigned*)op = pk2(a0, a1); *(unsigned*)(op + 2048) = pk2(b0, b1);
;             }
;             f32x4 ndl[4]; bf16x8 nvB[4];
;             SCAN_LREAD(nbuf, nvB, ndl);
; #pragma unroll
	v_lshlrev_b32_e32 v49, 16, v225
	v_lshlrev_b32_e32 v48, 16, v224
	v_pk_add_f32 v[228:229], v[228:229], v[48:49]
	v_and_b32_e32 v225, 0xffff0000, v225
	v_and_b32_e32 v224, 0xffff0000, v224
	v_pk_add_f32 v[230:231], v[230:231], v[224:225]
	v_lshlrev_b32_e32 v49, 16, v227
	v_lshlrev_b32_e32 v48, 16, v226
	v_pk_add_f32 v[228:229], v[228:229], v[48:49]
	v_and_b32_e32 v227, 0xffff0000, v227
	v_and_b32_e32 v226, 0xffff0000, v226
	v_pk_add_f32 v[230:231], v[230:231], v[226:227]
	v_cvt_pk_bf16_f32 v228, v228, v229
	v_cvt_pk_bf16_f32 v230, v230, v231
	global_store_dword v249, v228, s[38:39]
	global_store_dword v250, v230, s[38:39]
	s_add_u32 s38, s38, s55
	s_addc_u32 s39, s39, s56
	v_cvt_pk_bf16_f32 v48, v0, v1
	v_cvt_pk_bf16_f32 v49, v2, v3
	v_cvt_pk_bf16_f32 v50, v4, v5
	v_cvt_pk_bf16_f32 v51, v6, v7
	v_cvt_pk_bf16_f32 v52, v8, v9
	v_cvt_pk_bf16_f32 v53, v10, v11
	v_cvt_pk_bf16_f32 v54, v12, v13
	v_cvt_pk_bf16_f32 v55, v14, v15
	v_mfma_f32_32x32x16_bf16 v[16:31], v[56:59], v[48:51], 0
	v_pk_mul_f32 v[0:1], v[162:163], v[0:1]
	v_pk_mul_f32 v[2:3], v[164:165], v[2:3]
	v_pk_mul_f32 v[4:5], v[166:167], v[4:5]
	v_mfma_f32_32x32x16_bf16 v[32:47], v[64:67], v[48:51], 0
	v_pk_mul_f32 v[6:7], v[168:169], v[6:7]
	v_pk_mul_f32 v[8:9], v[170:171], v[8:9]
	v_pk_mul_f32 v[10:11], v[172:173], v[10:11]
	v_mfma_f32_32x32x16_bf16 v[16:31], v[60:63], v[52:55], v[16:31]
	v_pk_mul_f32 v[12:13], v[174:175], v[12:13]
	v_pk_mul_f32 v[14:15], v[176:177], v[14:15]
	v_mfma_f32_32x32x16_bf16 v[32:47], v[68:71], v[52:55], v[32:47]
	v_mfma_f32_32x32x16_bf16 v[16:31], v[72:75], v[196:199], v[16:31]
	v_mfma_f32_32x32x16_bf16 v[0:15], v[76:79], v[128:131], v[0:15]
	v_mfma_f32_32x32x16_bf16 v[0:15], v[80:83], v[132:135], v[0:15]
	v_mfma_f32_32x32x16_bf16 v[0:15], v[84:87], v[136:139], v[0:15]
	v_mfma_f32_32x32x16_bf16 v[0:15], v[88:91], v[140:143], v[0:15]
	ds_read_b128 v[144:147], v246 offset:4096
	global_load_dwordx4 v[76:79], v235, s[32:33]
	ds_read_b128 v[148:151], v246 offset:5120
	ds_read_b128 v[152:155], v246 offset:6144
	ds_read_b128 v[156:159], v246 offset:7168
	ds_read_b128 v[200:203], v248 offset:4096
	global_load_dwordx4 v[80:83], v235, s[32:33] offset:1024
	ds_read_b128 v[178:181], v247 offset:1024
	ds_read_b128 v[182:185], v247 offset:1056
	ds_read_b128 v[186:189], v247 offset:1088
	ds_read_b128 v[190:193], v247 offset:1120
	global_load_dwordx4 v[84:87], v235, s[32:33] offset:2048
	v_cvt_pk_bf16_f32 v16, v16, v17
	v_cvt_pk_bf16_f32 v18, v18, v19
	v_cvt_pk_bf16_f32 v20, v20, v21
	global_load_dwordx4 v[88:91], v235, s[32:33] offset:3072
	v_cvt_pk_bf16_f32 v22, v22, v23
	v_cvt_pk_bf16_f32 v24, v24, v25
	v_cvt_pk_bf16_f32 v26, v26, v27
	v_cvt_pk_bf16_f32 v28, v28, v29
	global_load_dwordx4 v[56:59], v232, s[34:35] offset:-4096
	v_cvt_pk_bf16_f32 v30, v30, v31
	ds_write2st64_b32 v241, v16, v20 offset0:0 offset1:2
	ds_write2st64_b32 v242, v18, v22 offset0:1 offset1:3
	ds_write2st64_b32 v241, v24, v28 offset0:4 offset1:6
	global_load_dwordx4 v[60:63], v232, s[34:35]
	ds_write2st64_b32 v242, v26, v30 offset0:5 offset1:7
	v_cvt_pk_bf16_f32 v32, v32, v33
	v_cvt_pk_bf16_f32 v34, v34, v35
	global_load_dwordx4 v[64:67], v233, s[34:35] offset:-4096
	v_cvt_pk_bf16_f32 v36, v36, v37
	v_cvt_pk_bf16_f32 v38, v38, v39
	v_cvt_pk_bf16_f32 v40, v40, v41
	v_cvt_pk_bf16_f32 v42, v42, v43
	global_load_dwordx4 v[68:71], v233, s[34:35]
	v_cvt_pk_bf16_f32 v44, v44, v45
	v_cvt_pk_bf16_f32 v46, v46, v47
	ds_write2st64_b32 v243, v32, v36 offset0:0 offset1:2
	ds_write2st64_b32 v244, v34, v38 offset0:1 offset1:3
	global_load_dwordx4 v[72:75], v251, s[36:37]
	ds_write2st64_b32 v243, v40, v44 offset0:4 offset1:6
	ds_write2st64_b32 v244, v42, v46 offset0:5 offset1:7
	s_add_u32 s32, s32, s53
	s_addc_u32 s33, s33, s56
	s_add_u32 s34, s34, s53
	s_addc_u32 s35, s35, s56
	s_add_u32 s36, s36, s54
	s_addc_u32 s37, s37, s56
	s_waitcnt lgkmcnt(0)
	s_barrier
	s_waitcnt vmcnt(12)
	ds_write_b128 v240, v[208:211]
	global_load_dwordx4 v[208:211], v[194:195], off
	v_lshl_add_u64 v[194:195], v[194:195], 0, v[254:255]
	ds_read2st64_b64 v[212:215], v245 offset0:0 offset1:8
	ds_read2st64_b64 v[216:219], v245 offset0:16 offset1:24
	ds_read2st64_b64 v[220:223], v245 offset0:32 offset1:40
	ds_read2st64_b64 v[224:227], v245 offset0:48 offset1:56
	s_waitcnt lgkmcnt(3)
	v_lshlrev_b32_e32 v229, 16, v213
	v_lshlrev_b32_e32 v228, 16, v212
	v_pk_add_f32 v[228:229], v[228:229], 0 op_sel_hi:[1,0]
	v_and_b32_e32 v231, 0xffff0000, v213
	v_and_b32_e32 v230, 0xffff0000, v212
	v_pk_add_f32 v[230:231], v[230:231], 0 op_sel_hi:[1,0]
	v_lshlrev_b32_e32 v49, 16, v215
	v_lshlrev_b32_e32 v48, 16, v214
	v_pk_add_f32 v[228:229], v[228:229], v[48:49]
	v_and_b32_e32 v215, 0xffff0000, v215
	v_and_b32_e32 v214, 0xffff0000, v214
	v_pk_add_f32 v[230:231], v[230:231], v[214:215]
	s_waitcnt lgkmcnt(2)
	v_lshlrev_b32_e32 v49, 16, v217
	v_lshlrev_b32_e32 v48, 16, v216
	v_pk_add_f32 v[228:229], v[228:229], v[48:49]
	v_and_b32_e32 v217, 0xffff0000, v217
	v_and_b32_e32 v216, 0xffff0000, v216
	v_pk_add_f32 v[230:231], v[230:231], v[216:217]
	v_lshlrev_b32_e32 v49, 16, v219
	v_lshlrev_b32_e32 v48, 16, v218
	v_pk_add_f32 v[228:229], v[228:229], v[48:49]
	v_and_b32_e32 v219, 0xffff0000, v219
	v_and_b32_e32 v218, 0xffff0000, v218
	v_pk_add_f32 v[230:231], v[230:231], v[218:219]
	s_waitcnt lgkmcnt(1)
	v_lshlrev_b32_e32 v49, 16, v221
	v_lshlrev_b32_e32 v48, 16, v220
	v_pk_add_f32 v[228:229], v[228:229], v[48:49]
	v_and_b32_e32 v221, 0xffff0000, v221
	v_and_b32_e32 v220, 0xffff0000, v220
	v_pk_add_f32 v[230:231], v[230:231], v[220:221]
	v_lshlrev_b32_e32 v49, 16, v223
	v_lshlrev_b32_e32 v48, 16, v222
	v_pk_add_f32 v[228:229], v[228:229], v[48:49]
	v_and_b32_e32 v223, 0xffff0000, v223
	v_and_b32_e32 v222, 0xffff0000, v222
	v_pk_add_f32 v[230:231], v[230:231], v[222:223]
	s_waitcnt lgkmcnt(0)
; __device__ __forceinline__ void phase_scan(const Args& a, unsigned char* smem, int tid, int lane, int wave) {
;     ...
;             const int rbuf = step & 1, nbuf = rbuf ^ 1;
;             if (gc < 512) {
;                 u32x4 s0, s1;
;                 s0.x = pk2(S[0], S[1]); s0.y = pk2(S[2], S[3]); s0.z = pk2(S[4], S[5]); s0.w = pk2(S[6], S[7]);
;                 s1.x = pk2(S[8], S[9]); s1.y = pk2(S[10], S[11]); s1.z = pk2(S[12], S[13]); s1.w = pk2(S[14], S[15]);
;                 const bf16x8 sb0 = __builtin_bit_cast(bf16x8, s0), sb1 = __builtin_bit_cast(bf16x8, s1);
;                 f32x16 o0, o1;
; #pragma unroll
;                 for (int i = 0; i < 16; ++i) { o0[i] = 0.f; o1[i] = 0.f; }
;                 o0 = mfma32(qeA[0], sb0, o0); o0 = mfma32(qeA[1], sb1, o0);
;                 o1 = mfma32(qeA[2], sb0, o1); o1 = mfma32(qeA[3], sb1, o1);
;                 const int w3 = wave & 3;
;                 const bf16x8 vs = w3 == 0 ? vB[0] : (w3 == 1 ? vB[1] : (w3 == 2 ? vB[2] : vB[3]));
;                 if (wave < 4) o0 = mfma32(atA, vs, o0); else o1 = mfma32(atA, vs, o1);
;                 unsigned* rb = red + (size_t)(rbuf * 8 + wave) * 1024 + lane; unsigned* rbx = red + (size_t)(rbuf * 8 + wave) * 1024 + (lane ^ 32);
; #pragma unroll
;                 for (int i = 0; i < 8; ++i) { unsigned* w_ = (i & 1) ? rbx : rb; w_[i * 64] = pk2(o0[2 * i], o0[2 * i + 1]); w_[512 + i * 64] = pk2(o1[2 * i], o1[2 * i + 1]); }
;             }
;             SCAN_GSTORE(nbuf, gcur);
;             __syncthreads();
;             if (gc < 512) {
;                 const int tp = tid >> 4, dv2 = (tid & 15) * 2, t = tp * 2, mt = t >> 5, tl = t & 31, pi = 2 * (tl >> 3) + ((tl & 3) >> 1), ln = ((tl >> 2) & 1) * 32 + dv2;
;                 const unsigned* rp = red + (size_t)rbuf * 8192 + (mt * 8 + pi) * 64 + (ln ^ ((pi & 1) << 5));
;                 float a0 = 0.f, a1 = 0.f, b0 = 0.f, b1 = 0.f;
; #pragma unroll
;                 for (int w = 0; w < 8; ++w) { const u32x2 v = *(const u32x2*)(rp + w * 1024); a0 += bflo(v.x); b0 += bfhi(v.x); a1 += bflo(v.y); b1 += bfhi(v.y); }
;                 bf16_t* op = O + (row0 + t) * 2048 + h * 512 + sl * 32 + dv2;
;                 *(unsigned*)op = pk2(a0, a1); *(unsigned*)(op + 2048) = pk2(b0, b1);
;             }
;             f32x4 ndl[4]; bf16x8 nvB[4];
;             SCAN_LREAD(nbuf, nvB, ndl);
; #pragma unroll
	v_lshlrev_b32_e32 v49, 16, v225
	v_lshlrev_b32_e32 v48, 16, v224
	v_pk_add_f32 v[228:229], v[228:229], v[48:49]
	v_and_b32_e32 v225, 0xffff0000, v225
	v_and_b32_e32 v224, 0xffff0000, v224
	v_pk_add_f32 v[230:231], v[230:231], v[224:225]
	v_lshlrev_b32_e32 v49, 16, v227
	v_lshlrev_b32_e32 v48, 16, v226
	v_pk_add_f32 v[228:229], v[228:229], v[48:49]
	v_and_b32_e32 v227, 0xffff0000, v227
	v_and_b32_e32 v226, 0xffff0000, v226
	v_pk_add_f32 v[230:231], v[230:231], v[226:227]
	v_cvt_pk_bf16_f32 v228, v228, v229
	v_cvt_pk_bf16_f32 v230, v230, v231
	global_store_dword v249, v228, s[38:39]
	global_store_dword v250, v230, s[38:39]
	s_add_u32 s38, s38, s55
	s_addc_u32 s39, s39, s56
	v_cvt_pk_bf16_f32 v48, v0, v1
	v_cvt_pk_bf16_f32 v49, v2, v3
	v_cvt_pk_bf16_f32 v50, v4, v5
	v_cvt_pk_bf16_f32 v51, v6, v7
	v_cvt_pk_bf16_f32 v52, v8, v9
	v_cvt_pk_bf16_f32 v53, v10, v11
	v_cvt_pk_bf16_f32 v54, v12, v13
	v_cvt_pk_bf16_f32 v55, v14, v15
	v_mfma_f32_32x32x16_bf16 v[16:31], v[92:95], v[48:51], 0
	v_pk_mul_f32 v[0:1], v[178:179], v[0:1]
	v_pk_mul_f32 v[2:3], v[180:181], v[2:3]
	v_pk_mul_f32 v[4:5], v[182:183], v[4:5]
	v_mfma_f32_32x32x16_bf16 v[32:47], v[100:103], v[48:51], 0
	v_pk_mul_f32 v[6:7], v[184:185], v[6:7]
	v_pk_mul_f32 v[8:9], v[186:187], v[8:9]
	v_pk_mul_f32 v[10:11], v[188:189], v[10:11]
	v_mfma_f32_32x32x16_bf16 v[16:31], v[96:99], v[52:55], v[16:31]
	v_pk_mul_f32 v[12:13], v[190:191], v[12:13]
	v_pk_mul_f32 v[14:15], v[192:193], v[14:15]
	v_mfma_f32_32x32x16_bf16 v[32:47], v[104:107], v[52:55], v[32:47]
	v_mfma_f32_32x32x16_bf16 v[16:31], v[108:111], v[200:203], v[16:31]
	v_mfma_f32_32x32x16_bf16 v[0:15], v[112:115], v[144:147], v[0:15]
	v_mfma_f32_32x32x16_bf16 v[0:15], v[116:119], v[148:151], v[0:15]
	v_mfma_f32_32x32x16_bf16 v[0:15], v[120:123], v[152:155], v[0:15]
	v_mfma_f32_32x32x16_bf16 v[0:15], v[124:127], v[156:159], v[0:15]
	ds_read_b128 v[128:131], v246 offset:0
	global_load_dwordx4 v[112:115], v235, s[32:33]
	ds_read_b128 v[132:135], v246 offset:1024
	ds_read_b128 v[136:139], v246 offset:2048
	ds_read_b128 v[140:143], v246 offset:3072
	ds_read_b128 v[196:199], v248 offset:0
	global_load_dwordx4 v[116:119], v235, s[32:33] offset:1024
	ds_read_b128 v[162:165], v247 offset:0
	ds_read_b128 v[166:169], v247 offset:32
	ds_read_b128 v[170:173], v247 offset:64
	ds_read_b128 v[174:177], v247 offset:96
	global_load_dwordx4 v[120:123], v235, s[32:33] offset:2048
	v_cvt_pk_bf16_f32 v16, v16, v17
	v_cvt_pk_bf16_f32 v18, v18, v19
	v_cvt_pk_bf16_f32 v20, v20, v21
	global_load_dwordx4 v[124:127], v235, s[32:33] offset:3072
	v_cvt_pk_bf16_f32 v22, v22, v23
	v_cvt_pk_bf16_f32 v24, v24, v25
	v_cvt_pk_bf16_f32 v26, v26, v27
	v_cvt_pk_bf16_f32 v28, v28, v29
	global_load_dwordx4 v[92:95], v232, s[34:35] offset:-4096
	v_cvt_pk_bf16_f32 v30, v30, v31
	ds_write2st64_b32 v241, v16, v20 offset0:128 offset1:130
	ds_write2st64_b32 v242, v18, v22 offset0:129 offset1:131
	ds_write2st64_b32 v241, v24, v28 offset0:132 offset1:134
	global_load_dwordx4 v[96:99], v232, s[34:35]
	ds_write2st64_b32 v242, v26, v30 offset0:133 offset1:135
	v_cvt_pk_bf16_f32 v32, v32, v33
	v_cvt_pk_bf16_f32 v34, v34, v35
	global_load_dwordx4 v[100:103], v233, s[34:35] offset:-4096
	v_cvt_pk_bf16_f32 v36, v36, v37
	v_cvt_pk_bf16_f32 v38, v38, v39
	v_cvt_pk_bf16_f32 v40, v40, v41
	v_cvt_pk_bf16_f32 v42, v42, v43
	global_load_dwordx4 v[104:107], v233, s[34:35]
	v_cvt_pk_bf16_f32 v44, v44, v45
	v_cvt_pk_bf16_f32 v46, v46, v47
	ds_write2st64_b32 v243, v32, v36 offset0:128 offset1:130
	ds_write2st64_b32 v244, v34, v38 offset0:129 offset1:131
	global_load_dwordx4 v[108:111], v251, s[36:37]
	ds_write2st64_b32 v243, v40, v44 offset0:132 offset1:134
	ds_write2st64_b32 v244, v42, v46 offset0:133 offset1:135
	s_add_u32 s32, s32, s53
	s_addc_u32 s33, s33, s56
	s_add_u32 s34, s34, s53
	s_addc_u32 s35, s35, s56
	s_add_u32 s36, s36, s54
	s_addc_u32 s37, s37, s56
	s_waitcnt lgkmcnt(0)
	s_barrier
	s_add_i32 s30, s30, 2
	s_cmp_lt_u32 s30, 256
	s_cbranch_scc1 .Lscan_loopB
.Lscan_join:
	ds_read2st64_b64 v[212:215], v245 offset0:64 offset1:72
	ds_read2st64_b64 v[216:219], v245 offset0:80 offset1:88
	ds_read2st64_b64 v[220:223], v245 offset0:96 offset1:104
	ds_read2st64_b64 v[224:227], v245 offset0:112 offset1:120
	s_waitcnt lgkmcnt(3)
	v_lshlrev_b32_e32 v229, 16, v213
	v_lshlrev_b32_e32 v228, 16, v212
	v_pk_add_f32 v[228:229], v[228:229], 0 op_sel_hi:[1,0]
	v_and_b32_e32 v231, 0xffff0000, v213
	v_and_b32_e32 v230, 0xffff0000, v212
	v_pk_add_f32 v[230:231], v[230:231], 0 op_sel_hi:[1,0]
	v_lshlrev_b32_e32 v49, 16, v215
	v_lshlrev_b32_e32 v48, 16, v214
	v_pk_add_f32 v[228:229], v[228:229], v[48:49]
	v_and_b32_e32 v215, 0xffff0000, v215
	v_and_b32_e32 v214, 0xffff0000, v214
	v_pk_add_f32 v[230:231], v[230:231], v[214:215]
	s_waitcnt lgkmcnt(2)
	v_lshlrev_b32_e32 v49, 16, v217
	v_lshlrev_b32_e32 v48, 16, v216
	v_pk_add_f32 v[228:229], v[228:229], v[48:49]
	v_and_b32_e32 v217, 0xffff0000, v217
	v_and_b32_e32 v216, 0xffff0000, v216
	v_pk_add_f32 v[230:231], v[230:231], v[216:217]
	v_lshlrev_b32_e32 v49, 16, v219
	v_lshlrev_b32_e32 v48, 16, v218
	v_pk_add_f32 v[228:229], v[228:229], v[48:49]
	v_and_b32_e32 v219, 0xffff0000, v219
	v_and_b32_e32 v218, 0xffff0000, v218
	v_pk_add_f32 v[230:231], v[230:231], v[218:219]
	s_waitcnt lgkmcnt(1)
	v_lshlrev_b32_e32 v49, 16, v221
	v_lshlrev_b32_e32 v48, 16, v220
	v_pk_add_f32 v[228:229], v[228:229], v[48:49]
	v_and_b32_e32 v221, 0xffff0000, v221
	v_and_b32_e32 v220, 0xffff0000, v220
	v_pk_add_f32 v[230:231], v[230:231], v[220:221]
	v_lshlrev_b32_e32 v49, 16, v223
	v_lshlrev_b32_e32 v48, 16, v222
	v_pk_add_f32 v[228:229], v[228:229], v[48:49]
	v_and_b32_e32 v223, 0xffff0000, v223
	v_and_b32_e32 v222, 0xffff0000, v222
	v_pk_add_f32 v[230:231], v[230:231], v[222:223]
	s_waitcnt lgkmcnt(0)
	v_lshlrev_b32_e32 v49, 16, v225
	v_lshlrev_b32_e32 v48, 16, v224
	v_pk_add_f32 v[228:229], v[228:229], v[48:49]
	v_and_b32_e32 v225, 0xffff0000, v225
	v_and_b32_e32 v224, 0xffff0000, v224
	v_pk_add_f32 v[230:231], v[230:231], v[224:225]
	v_lshlrev_b32_e32 v49, 16, v227
	v_lshlrev_b32_e32 v48, 16, v226
	v_pk_add_f32 v[228:229], v[228:229], v[48:49]
	v_and_b32_e32 v227, 0xffff0000, v227
	v_and_b32_e32 v226, 0xffff0000, v226
	v_pk_add_f32 v[230:231], v[230:231], v[226:227]
	v_cvt_pk_bf16_f32 v228, v228, v229
	v_cvt_pk_bf16_f32 v230, v230, v231
	global_store_dword v249, v228, s[38:39]
	global_store_dword v250, v230, s[38:39]
	s_add_u32 s38, s38, s55
	s_addc_u32 s39, s39, s56
	s_waitcnt vmcnt(0) lgkmcnt(0)
	s_barrier
.Lscan_skipunit:
	v_readlane_b32 s50, v252, 0
	v_readlane_b32 s51, v252, 1
	s_nop 3
	s_load_dword s40, s[50:51], 0x98
	s_waitcnt lgkmcnt(0)
	s_add_i32 s14, s14, s40
	s_cmpk_lt_i32 s14, 0x100
	s_cbranch_scc1 .Lscan_unit
